# mixer second slot: stage-in counter snapshot read early (mid first-slot conformer part) and tested before polling
# baseline (speedup 1.0000x reference)
.LBB0_512:
	v_cmp_eq_u32_e64 s[4:5], 0, v146
	s_cmp_lt_i32 s39, 1
	s_nop 0
	v_writelane_b32 v254, s4, 50
	s_nop 1
	v_writelane_b32 v254, s5, 51
	v_writelane_b32 v254, s56, 52
	s_nop 1
	v_writelane_b32 v254, s57, 53
	s_cbranch_scc1 .LBB0_665
	v_readlane_b32 s4, v252, 7
	s_add_i32 s33, s33, s4
	s_add_u32 s4, s44, 0x300000
	s_addc_u32 s5, s45, 0
	v_writelane_b32 v254, s4, 54
	s_mov_b32 s25, s97
	s_mul_i32 s23, s56, 0x7c00
	v_writelane_b32 v254, s5, 55
	s_add_u32 s4, s44, 0x380000
	s_addc_u32 s5, s45, 0
	v_writelane_b32 v254, s4, 56
	s_mov_b32 s40, 0
	s_mov_b64 s[58:59], 0
	v_writelane_b32 v254, s5, 57
	s_add_u32 s4, s44, 0x1e00000
	s_addc_u32 s5, s45, 0
	s_cmp_gt_i32 s38, 31
	v_writelane_b32 v254, s4, 58
	s_cselect_b64 s[34:35], -1, 0
	s_cmp_gt_u32 s38, 63
	v_writelane_b32 v254, s5, 59
	s_cselect_b64 s[4:5], -1, 0
	v_writelane_b32 v254, s4, 60
	s_cmpk_gt_u32 s38, 0x9f
	s_nop 0
	v_writelane_b32 v254, s5, 61
	s_cselect_b64 s[4:5], -1, 0
	v_writelane_b32 v254, s4, 62
	s_lshl_b32 s96, s56, 6
	s_add_i32 s22, s38, 32
	v_writelane_b32 v254, s5, 63
	s_lshl_b32 s4, s38, 1
	s_add_i32 s5, s4, 0xffffff7e
	v_writelane_b32 v255, s5, 0
	v_writelane_b32 v255, s4, 1
	s_sub_i32 s4, s4, 33
	v_writelane_b32 v255, s4, 2
	s_lshl_b64 s[4:5], s[96:97], 2
	s_add_u32 s4, s44, s4
	s_addc_u32 s5, s45, s5
	s_add_u32 s28, s4, 0x8000
	s_addc_u32 s29, s5, 0
	s_mov_b64 s[66:67], exec
	s_mov_b64 exec, -1
	v_mov_b32_e32 v250, 0
	s_mov_b64 exec, s[66:67]
	s_lshl_b32 s24, s56, 8
	s_lshl_b64 s[4:5], s[24:25], 2
	s_add_u32 s36, s92, s4
	s_addc_u32 s37, s93, s5
	v_writelane_b32 v255, s36, 3
	s_nop 1
	v_writelane_b32 v255, s37, 4
	s_add_u32 s36, s94, s4
	s_addc_u32 s37, s95, s5
	v_writelane_b32 v255, s36, 5
	s_add_u32 s4, s26, s4
	s_addc_u32 s5, s27, s5
	v_writelane_b32 v255, s37, 6
	v_writelane_b32 v255, s4, 7
	s_nop 1
	v_writelane_b32 v255, s5, 8
	s_add_u32 s4, s44, 0x1e00600
	s_addc_u32 s5, s45, 0
	v_writelane_b32 v255, s4, 9
	s_nop 1
	v_writelane_b32 v255, s5, 10
	s_add_u32 s4, s44, 0x1e00400
	s_addc_u32 s5, s45, 0
	s_add_u32 s25, s44, 0x40000
	s_addc_u32 s41, s45, 0
	s_lshl_b32 s36, s56, 13
	v_writelane_b32 v255, s4, 11
	s_add_u32 s90, s90, s23
	s_addc_u32 s91, s91, 0
	v_writelane_b32 v255, s5, 12
	s_mov_b64 s[56:57], 0
	s_mov_b64 s[26:27], -1
	s_and_b64 vcc, exec, s[30:31]
	s_cbranch_vccz .LBB0_515

.LBB0_543:
	s_mov_b64 s[26:27], exec
	v_readlane_b32 s42, v254, 50
	v_readlane_b32 s43, v254, 51
	s_and_b64 s[42:43], s[26:27], s[42:43]
	s_mov_b64 exec, s[42:43]
	s_cbranch_execz .LBB0_556
	s_waitcnt vmcnt(0)
	v_cmp_le_u32_e32 vcc, s33, v250
	s_cbranch_vccnz .LBB0_555
	global_load_dword v0, v149, s[28:29] sc1
	s_waitcnt vmcnt(0)
	v_cmp_le_u32_e32 vcc, s33, v0
	s_cbranch_vccnz .LBB0_555
	s_mov_b32 s4, 0xffff8
	s_branch .LBB0_547

.LBB0_593:
	s_or_b64 exec, exec, s[26:27]
	s_ashr_i32 s27, s66, 6
	s_lshl_b32 s26, s27, 5
	v_and_b32_e32 v158, 15, v156
	s_add_i32 s23, s26, s24
	v_or_b32_e32 v0, s23, v158
	v_ashrrev_i32_e32 v1, 31, v0
	v_readlane_b32 s42, v254, 56
	v_lshlrev_b64 v[0:1], 9, v[0:1]
	v_readlane_b32 s43, v254, 57
	v_and_b32_e32 v148, 48, v156
	v_ashrrev_i32_e32 v166, 3, v156
	v_lshl_add_u64 v[0:1], s[42:43], 0, v[0:1]
	v_lshl_add_u64 v[0:1], v[0:1], 0, v[148:149]
	v_and_b32_e32 v159, -16, v166
	v_lshl_add_u32 v167, v157, 2, 0
	v_add_co_u32_e32 v2, vcc, 0x2000, v0
	v_lshl_add_u32 v161, v159, 9, v167
	s_nop 0
	v_addc_co_u32_e32 v3, vcc, 0, v1, vcc
	global_load_dwordx4 v[56:59], v[0:1], off
	global_load_dwordx4 v[48:51], v[0:1], off offset:64
	global_load_dwordx4 v[60:63], v[2:3], off
	global_load_dwordx4 v[52:55], v[2:3], off offset:64
	global_load_dwordx4 v[40:43], v[0:1], off offset:128
	global_load_dwordx4 v[32:35], v[0:1], off offset:192
	global_load_dwordx4 v[44:47], v[2:3], off offset:128
	global_load_dwordx4 v[36:39], v[2:3], off offset:192
	global_load_dwordx4 v[24:27], v[0:1], off offset:256
	global_load_dwordx4 v[16:19], v[0:1], off offset:320
	global_load_dwordx4 v[28:31], v[2:3], off offset:256
	global_load_dwordx4 v[20:23], v[2:3], off offset:320
	v_mov_b32_e32 v248, v161
	ds_read_b32 v244, v248
	ds_read_b32 v245, v248 offset:512
	ds_read_b32 v246, v248 offset:1024
	ds_read_b32 v247, v248 offset:1536
	v_or_b32_e32 v160, 1, v159
	v_mov_b64_e32 v[164:165], v[126:127]
	v_mov_b64_e32 v[168:169], v[126:127]
	v_mov_b64_e32 v[170:171], v[126:127]
	s_waitcnt lgkmcnt(3)
	v_mov_b32_e32 v129, v244
	v_lshlrev_b32_e32 v128, 16, v129
	v_and_b32_e32 v129, 0xffff0000, v129
	v_pk_fma_f32 v[162:163], v[124:125], v[128:129], v[126:127]
	v_mov_b64_e32 v[172:173], v[126:127]
	v_mov_b64_e32 v[174:175], v[126:127]
	v_mov_b64_e32 v[144:145], v[126:127]
	v_mov_b64_e32 v[142:143], v[126:127]
	v_mov_b64_e32 v[140:141], v[126:127]
	v_mov_b64_e32 v[138:139], v[126:127]
	v_mov_b64_e32 v[136:137], v[126:127]
	v_mov_b64_e32 v[134:135], v[126:127]
	v_mov_b64_e32 v[132:133], v[126:127]
	v_mov_b64_e32 v[130:131], v[126:127]
	v_mov_b64_e32 v[128:129], v[126:127]
	v_lshl_add_u32 v154, v160, 9, v167
	global_load_dwordx4 v[8:11], v[0:1], off offset:384
	global_load_dwordx4 v[4:7], v[0:1], off offset:448
	global_load_dwordx4 v[12:15], v[2:3], off offset:384
	s_nop 0
	global_load_dwordx4 v[0:3], v[2:3], off offset:448
	ds_read_b32 v244, v248 offset:2048
	v_readlane_b32 s42, v255, 5
	v_readlane_b32 s43, v255, 6
	s_lshl_b32 s23, s27, 13
	s_add_i32 s23, s23, 0
	s_waitcnt lgkmcnt(3)
	v_mov_b32_e32 v154, v245
	v_lshlrev_b32_e32 v176, 16, v154
	v_and_b32_e32 v177, 0xffff0000, v154
	v_pk_fma_f32 v[162:163], v[122:123], v[176:177], v[162:163]
	v_pk_fma_f32 v[176:177], v[124:125], v[176:177], v[126:127]
	v_or_b32_e32 v126, 2, v159
	v_lshl_add_u32 v127, v126, 9, v167
	ds_read_b32 v245, v248 offset:2560
	s_mov_b32 s46, 0x3b800000
	s_waitcnt lgkmcnt(3)
	v_mov_b32_e32 v127, v246
	v_lshlrev_b32_e32 v178, 16, v127
	v_and_b32_e32 v179, 0xffff0000, v127
	v_or_b32_e32 v127, 3, v159
	v_pk_fma_f32 v[162:163], v[120:121], v[178:179], v[162:163]
	v_pk_fma_f32 v[176:177], v[122:123], v[178:179], v[176:177]
	v_pk_fma_f32 v[164:165], v[124:125], v[178:179], v[164:165]
	v_lshl_add_u32 v154, v127, 9, v167
	ds_read_b32 v246, v248 offset:3072
	s_waitcnt lgkmcnt(3)
	v_mov_b32_e32 v154, v247
	v_lshlrev_b32_e32 v178, 16, v154
	v_and_b32_e32 v179, 0xffff0000, v154
	v_pk_fma_f32 v[180:181], v[118:119], v[178:179], v[162:163]
	v_or_b32_e32 v162, 4, v159
	v_pk_fma_f32 v[176:177], v[120:121], v[178:179], v[176:177]
	v_pk_fma_f32 v[164:165], v[122:123], v[178:179], v[164:165]
	v_pk_fma_f32 v[168:169], v[124:125], v[178:179], v[168:169]
	v_lshl_add_u32 v154, v162, 9, v167
	ds_read_b32 v247, v248 offset:3584
	v_or_b32_e32 v163, 5, v159
	s_waitcnt lgkmcnt(3)
	v_mov_b32_e32 v154, v244
	v_lshlrev_b32_e32 v178, 16, v154
	v_and_b32_e32 v179, 0xffff0000, v154
	v_pk_fma_f32 v[180:181], v[116:117], v[178:179], v[180:181]
	v_pk_fma_f32 v[176:177], v[118:119], v[178:179], v[176:177]
	v_pk_fma_f32 v[164:165], v[120:121], v[178:179], v[164:165]
	v_pk_fma_f32 v[168:169], v[122:123], v[178:179], v[168:169]
	v_pk_fma_f32 v[170:171], v[124:125], v[178:179], v[170:171]
	v_lshl_add_u32 v154, v163, 9, v167
	ds_read_b32 v244, v248 offset:4096
	s_waitcnt lgkmcnt(3)
	v_mov_b32_e32 v154, v245
	v_lshlrev_b32_e32 v178, 16, v154
	v_and_b32_e32 v179, 0xffff0000, v154
	v_pk_fma_f32 v[182:183], v[118:119], v[178:179], v[164:165]
	v_or_b32_e32 v164, 6, v159
	v_pk_fma_f32 v[180:181], v[114:115], v[178:179], v[180:181]
	v_pk_fma_f32 v[176:177], v[116:117], v[178:179], v[176:177]
	v_pk_fma_f32 v[168:169], v[120:121], v[178:179], v[168:169]
	v_pk_fma_f32 v[170:171], v[122:123], v[178:179], v[170:171]
	v_pk_fma_f32 v[172:173], v[124:125], v[178:179], v[172:173]
	v_lshl_add_u32 v154, v164, 9, v167
	ds_read_b32 v245, v248 offset:4608
	v_or_b32_e32 v165, 7, v159
	s_waitcnt lgkmcnt(3)
	v_mov_b32_e32 v154, v246
	v_lshlrev_b32_e32 v178, 16, v154
	v_and_b32_e32 v179, 0xffff0000, v154
	v_pk_fma_f32 v[180:181], v[112:113], v[178:179], v[180:181]
	v_pk_fma_f32 v[176:177], v[114:115], v[178:179], v[176:177]
	v_pk_fma_f32 v[182:183], v[116:117], v[178:179], v[182:183]
	v_pk_fma_f32 v[168:169], v[118:119], v[178:179], v[168:169]
	v_pk_fma_f32 v[170:171], v[120:121], v[178:179], v[170:171]
	v_pk_fma_f32 v[172:173], v[122:123], v[178:179], v[172:173]
	v_pk_fma_f32 v[174:175], v[124:125], v[178:179], v[174:175]
	v_lshl_add_u32 v154, v165, 9, v167
	ds_read_b32 v246, v248 offset:5120
	s_waitcnt lgkmcnt(3)
	v_mov_b32_e32 v154, v247
	v_lshlrev_b32_e32 v178, 16, v154
	v_and_b32_e32 v179, 0xffff0000, v154
	v_pk_fma_f32 v[180:181], v[110:111], v[178:179], v[180:181]
	v_pk_fma_f32 v[176:177], v[112:113], v[178:179], v[176:177]
	v_pk_fma_f32 v[182:183], v[114:115], v[178:179], v[182:183]
	v_pk_fma_f32 v[168:169], v[116:117], v[178:179], v[168:169]
	v_pk_fma_f32 v[170:171], v[118:119], v[178:179], v[170:171]
	v_pk_fma_f32 v[172:173], v[120:121], v[178:179], v[172:173]
	v_pk_fma_f32 v[174:175], v[122:123], v[178:179], v[174:175]
	v_pk_fma_f32 v[178:179], v[124:125], v[178:179], v[144:145]
	v_or_b32_e32 v144, 8, v159
	v_lshl_add_u32 v145, v144, 9, v167
	ds_read_b32 v247, v248 offset:5632
	s_waitcnt lgkmcnt(3)
	v_mov_b32_e32 v145, v244
	v_lshlrev_b32_e32 v184, 16, v145
	v_and_b32_e32 v185, 0xffff0000, v145
	v_pk_fma_f32 v[180:181], v[108:109], v[184:185], v[180:181]
	v_pk_fma_f32 v[176:177], v[110:111], v[184:185], v[176:177]
	v_pk_fma_f32 v[182:183], v[112:113], v[184:185], v[182:183]
	v_pk_fma_f32 v[168:169], v[114:115], v[184:185], v[168:169]
	v_pk_fma_f32 v[170:171], v[116:117], v[184:185], v[170:171]
	v_pk_fma_f32 v[172:173], v[118:119], v[184:185], v[172:173]
	v_pk_fma_f32 v[174:175], v[120:121], v[184:185], v[174:175]
	v_pk_fma_f32 v[178:179], v[122:123], v[184:185], v[178:179]
	v_pk_fma_f32 v[184:185], v[124:125], v[184:185], v[142:143]
	v_or_b32_e32 v142, 9, v159
	v_lshl_add_u32 v143, v142, 9, v167
	ds_read_b32 v244, v248 offset:6144
	s_waitcnt lgkmcnt(3)
	v_mov_b32_e32 v143, v245
	v_lshlrev_b32_e32 v186, 16, v143
	v_and_b32_e32 v187, 0xffff0000, v143
	v_pk_fma_f32 v[180:181], v[106:107], v[186:187], v[180:181]
	v_pk_fma_f32 v[176:177], v[108:109], v[186:187], v[176:177]
	v_pk_fma_f32 v[182:183], v[110:111], v[186:187], v[182:183]
	v_pk_fma_f32 v[168:169], v[112:113], v[186:187], v[168:169]
	v_pk_fma_f32 v[170:171], v[114:115], v[186:187], v[170:171]
	v_pk_fma_f32 v[172:173], v[116:117], v[186:187], v[172:173]
	v_pk_fma_f32 v[174:175], v[118:119], v[186:187], v[174:175]
	v_pk_fma_f32 v[178:179], v[120:121], v[186:187], v[178:179]
	v_pk_fma_f32 v[184:185], v[122:123], v[186:187], v[184:185]
	v_pk_fma_f32 v[186:187], v[124:125], v[186:187], v[140:141]
	v_or_b32_e32 v140, 10, v159
	v_lshl_add_u32 v141, v140, 9, v167
	ds_read_b32 v245, v248 offset:6656
	s_waitcnt lgkmcnt(3)
	v_mov_b32_e32 v141, v246
	v_lshlrev_b32_e32 v188, 16, v141
	v_and_b32_e32 v189, 0xffff0000, v141
	v_pk_fma_f32 v[180:181], v[104:105], v[188:189], v[180:181]
	v_pk_fma_f32 v[176:177], v[106:107], v[188:189], v[176:177]
	v_pk_fma_f32 v[182:183], v[108:109], v[188:189], v[182:183]
	v_pk_fma_f32 v[168:169], v[110:111], v[188:189], v[168:169]
	v_pk_fma_f32 v[170:171], v[112:113], v[188:189], v[170:171]
	v_pk_fma_f32 v[172:173], v[114:115], v[188:189], v[172:173]
	v_pk_fma_f32 v[174:175], v[116:117], v[188:189], v[174:175]
	v_pk_fma_f32 v[178:179], v[118:119], v[188:189], v[178:179]
	v_pk_fma_f32 v[184:185], v[120:121], v[188:189], v[184:185]
	v_pk_fma_f32 v[186:187], v[122:123], v[188:189], v[186:187]
	v_pk_fma_f32 v[188:189], v[124:125], v[188:189], v[138:139]
	v_or_b32_e32 v138, 11, v159
	v_lshl_add_u32 v139, v138, 9, v167
	ds_read_b32 v246, v248 offset:7168
	s_waitcnt lgkmcnt(3)
	v_mov_b32_e32 v139, v247
	v_lshlrev_b32_e32 v190, 16, v139
	v_and_b32_e32 v191, 0xffff0000, v139
	v_pk_fma_f32 v[180:181], v[102:103], v[190:191], v[180:181]
	v_pk_fma_f32 v[176:177], v[104:105], v[190:191], v[176:177]
	v_pk_fma_f32 v[182:183], v[106:107], v[190:191], v[182:183]
	v_pk_fma_f32 v[168:169], v[108:109], v[190:191], v[168:169]
	v_pk_fma_f32 v[170:171], v[110:111], v[190:191], v[170:171]
	v_pk_fma_f32 v[172:173], v[112:113], v[190:191], v[172:173]
	v_pk_fma_f32 v[174:175], v[114:115], v[190:191], v[174:175]
	v_pk_fma_f32 v[178:179], v[116:117], v[190:191], v[178:179]
	v_pk_fma_f32 v[184:185], v[118:119], v[190:191], v[184:185]
	v_pk_fma_f32 v[186:187], v[120:121], v[190:191], v[186:187]
	v_pk_fma_f32 v[188:189], v[122:123], v[190:191], v[188:189]
	v_pk_fma_f32 v[190:191], v[124:125], v[190:191], v[136:137]
	v_or_b32_e32 v136, 12, v159
	v_lshl_add_u32 v137, v136, 9, v167
	ds_read_b32 v247, v248 offset:7680
	s_waitcnt lgkmcnt(3)
	v_mov_b32_e32 v137, v244
	v_lshlrev_b32_e32 v192, 16, v137
	v_and_b32_e32 v193, 0xffff0000, v137
	v_pk_fma_f32 v[180:181], v[100:101], v[192:193], v[180:181]
	v_pk_fma_f32 v[176:177], v[102:103], v[192:193], v[176:177]
	v_pk_fma_f32 v[182:183], v[104:105], v[192:193], v[182:183]
	v_pk_fma_f32 v[168:169], v[106:107], v[192:193], v[168:169]
	v_pk_fma_f32 v[170:171], v[108:109], v[192:193], v[170:171]
	v_pk_fma_f32 v[172:173], v[110:111], v[192:193], v[172:173]
	v_pk_fma_f32 v[174:175], v[112:113], v[192:193], v[174:175]
	v_pk_fma_f32 v[178:179], v[114:115], v[192:193], v[178:179]
	v_pk_fma_f32 v[184:185], v[116:117], v[192:193], v[184:185]
	v_pk_fma_f32 v[186:187], v[118:119], v[192:193], v[186:187]
	v_pk_fma_f32 v[188:189], v[120:121], v[192:193], v[188:189]
	v_pk_fma_f32 v[190:191], v[122:123], v[192:193], v[190:191]
	v_pk_fma_f32 v[192:193], v[124:125], v[192:193], v[134:135]
	v_or_b32_e32 v134, 13, v159
	v_lshl_add_u32 v135, v134, 9, v167
	ds_read_b32 v244, v248 offset:8192
	s_waitcnt lgkmcnt(3)
	v_mov_b32_e32 v135, v245
	v_lshlrev_b32_e32 v194, 16, v135
	v_and_b32_e32 v195, 0xffff0000, v135
	v_pk_fma_f32 v[180:181], v[98:99], v[194:195], v[180:181]
	v_pk_fma_f32 v[176:177], v[100:101], v[194:195], v[176:177]
	v_pk_fma_f32 v[182:183], v[102:103], v[194:195], v[182:183]
	v_pk_fma_f32 v[168:169], v[104:105], v[194:195], v[168:169]
	v_pk_fma_f32 v[170:171], v[106:107], v[194:195], v[170:171]
	v_pk_fma_f32 v[172:173], v[108:109], v[194:195], v[172:173]
	v_pk_fma_f32 v[174:175], v[110:111], v[194:195], v[174:175]
	v_pk_fma_f32 v[178:179], v[112:113], v[194:195], v[178:179]
	v_pk_fma_f32 v[184:185], v[114:115], v[194:195], v[184:185]
	v_pk_fma_f32 v[186:187], v[116:117], v[194:195], v[186:187]
	v_pk_fma_f32 v[188:189], v[118:119], v[194:195], v[188:189]
	v_pk_fma_f32 v[190:191], v[120:121], v[194:195], v[190:191]
	v_pk_fma_f32 v[192:193], v[122:123], v[194:195], v[192:193]
	v_pk_fma_f32 v[194:195], v[124:125], v[194:195], v[132:133]
	v_or_b32_e32 v132, 14, v159
	v_lshl_add_u32 v133, v132, 9, v167
	ds_read_b32 v245, v248 offset:8704
	s_waitcnt lgkmcnt(3)
	v_mov_b32_e32 v133, v246
	v_lshlrev_b32_e32 v196, 16, v133
	v_and_b32_e32 v197, 0xffff0000, v133
	v_pk_fma_f32 v[180:181], v[96:97], v[196:197], v[180:181]
	v_pk_fma_f32 v[176:177], v[98:99], v[196:197], v[176:177]
	v_pk_fma_f32 v[182:183], v[100:101], v[196:197], v[182:183]
	v_pk_fma_f32 v[168:169], v[102:103], v[196:197], v[168:169]
	v_pk_fma_f32 v[170:171], v[104:105], v[196:197], v[170:171]
	v_pk_fma_f32 v[172:173], v[106:107], v[196:197], v[172:173]
	v_pk_fma_f32 v[174:175], v[108:109], v[196:197], v[174:175]
	v_pk_fma_f32 v[178:179], v[110:111], v[196:197], v[178:179]
	v_pk_fma_f32 v[184:185], v[112:113], v[196:197], v[184:185]
	v_pk_fma_f32 v[186:187], v[114:115], v[196:197], v[186:187]
	v_pk_fma_f32 v[188:189], v[116:117], v[196:197], v[188:189]
	v_pk_fma_f32 v[190:191], v[118:119], v[196:197], v[190:191]
	v_pk_fma_f32 v[192:193], v[120:121], v[196:197], v[192:193]
	v_pk_fma_f32 v[194:195], v[122:123], v[196:197], v[194:195]
	v_pk_fma_f32 v[196:197], v[124:125], v[196:197], v[130:131]
	v_or_b32_e32 v130, 15, v166
	v_lshl_add_u32 v131, v130, 9, v167
	ds_read_b32 v246, v248 offset:9216
	s_waitcnt lgkmcnt(3)
	v_mov_b32_e32 v131, v247
	v_lshlrev_b32_e32 v166, 16, v131
	v_and_b32_e32 v167, 0xffff0000, v131
	v_pk_fma_f32 v[180:181], v[94:95], v[166:167], v[180:181]
	v_pk_fma_f32 v[176:177], v[96:97], v[166:167], v[176:177]
	v_pk_fma_f32 v[182:183], v[98:99], v[166:167], v[182:183]
	v_pk_fma_f32 v[168:169], v[100:101], v[166:167], v[168:169]
	v_pk_fma_f32 v[170:171], v[102:103], v[166:167], v[170:171]
	v_pk_fma_f32 v[172:173], v[104:105], v[166:167], v[172:173]
	v_pk_fma_f32 v[174:175], v[106:107], v[166:167], v[174:175]
	v_pk_fma_f32 v[178:179], v[108:109], v[166:167], v[178:179]
	v_pk_fma_f32 v[184:185], v[110:111], v[166:167], v[184:185]
	v_pk_fma_f32 v[186:187], v[112:113], v[166:167], v[186:187]
	v_pk_fma_f32 v[188:189], v[114:115], v[166:167], v[188:189]
	v_pk_fma_f32 v[190:191], v[116:117], v[166:167], v[190:191]
	v_pk_fma_f32 v[192:193], v[118:119], v[166:167], v[192:193]
	v_pk_fma_f32 v[194:195], v[120:121], v[166:167], v[194:195]
	v_pk_fma_f32 v[196:197], v[122:123], v[166:167], v[196:197]
	v_pk_fma_f32 v[124:125], v[124:125], v[166:167], v[128:129]
	s_nop 0
	ds_read_b32 v247, v248 offset:9728
	s_waitcnt lgkmcnt(3)
	v_mov_b32_e32 v129, v244
	v_lshlrev_b32_e32 v128, 16, v129
	v_and_b32_e32 v129, 0xffff0000, v129
	v_pk_fma_f32 v[166:167], v[92:93], v[128:129], v[180:181]
	v_pk_fma_f32 v[176:177], v[94:95], v[128:129], v[176:177]
	v_pk_fma_f32 v[180:181], v[96:97], v[128:129], v[182:183]
	v_pk_fma_f32 v[168:169], v[98:99], v[128:129], v[168:169]
	v_pk_fma_f32 v[170:171], v[100:101], v[128:129], v[170:171]
	v_pk_fma_f32 v[172:173], v[102:103], v[128:129], v[172:173]
	v_pk_fma_f32 v[174:175], v[104:105], v[128:129], v[174:175]
	v_pk_fma_f32 v[178:179], v[106:107], v[128:129], v[178:179]
	v_pk_fma_f32 v[182:183], v[108:109], v[128:129], v[184:185]
	v_pk_fma_f32 v[184:185], v[110:111], v[128:129], v[186:187]
	v_pk_fma_f32 v[186:187], v[112:113], v[128:129], v[188:189]
	v_pk_fma_f32 v[188:189], v[114:115], v[128:129], v[190:191]
	v_pk_fma_f32 v[190:191], v[116:117], v[128:129], v[192:193]
	v_pk_fma_f32 v[192:193], v[118:119], v[128:129], v[194:195]
	v_pk_fma_f32 v[194:195], v[120:121], v[128:129], v[196:197]
	v_pk_fma_f32 v[122:123], v[122:123], v[128:129], v[124:125]
	s_nop 0
	ds_read_b32 v244, v248 offset:10240
	s_waitcnt lgkmcnt(3)
	v_mov_b32_e32 v125, v245
	v_lshlrev_b32_e32 v124, 16, v125
	v_and_b32_e32 v125, 0xffff0000, v125
	v_pk_fma_f32 v[128:129], v[90:91], v[124:125], v[166:167]
	v_pk_fma_f32 v[166:167], v[92:93], v[124:125], v[176:177]
	v_pk_fma_f32 v[176:177], v[94:95], v[124:125], v[180:181]
	v_pk_fma_f32 v[168:169], v[96:97], v[124:125], v[168:169]
	v_pk_fma_f32 v[170:171], v[98:99], v[124:125], v[170:171]
	v_pk_fma_f32 v[172:173], v[100:101], v[124:125], v[172:173]
	v_pk_fma_f32 v[174:175], v[102:103], v[124:125], v[174:175]
	v_pk_fma_f32 v[178:179], v[104:105], v[124:125], v[178:179]
	v_pk_fma_f32 v[180:181], v[106:107], v[124:125], v[182:183]
	v_pk_fma_f32 v[182:183], v[108:109], v[124:125], v[184:185]
	v_pk_fma_f32 v[184:185], v[110:111], v[124:125], v[186:187]
	v_pk_fma_f32 v[186:187], v[112:113], v[124:125], v[188:189]
	v_pk_fma_f32 v[188:189], v[114:115], v[124:125], v[190:191]
	v_pk_fma_f32 v[190:191], v[116:117], v[124:125], v[192:193]
	v_pk_fma_f32 v[192:193], v[118:119], v[124:125], v[194:195]
	v_pk_fma_f32 v[120:121], v[120:121], v[124:125], v[122:123]
	s_nop 0
	ds_read_b32 v245, v248 offset:10752
	s_waitcnt lgkmcnt(3)
	v_mov_b32_e32 v123, v246
	v_lshlrev_b32_e32 v122, 16, v123
	v_and_b32_e32 v123, 0xffff0000, v123
	v_pk_fma_f32 v[124:125], v[88:89], v[122:123], v[128:129]
	v_pk_fma_f32 v[128:129], v[90:91], v[122:123], v[166:167]
	v_pk_fma_f32 v[166:167], v[92:93], v[122:123], v[176:177]
	v_pk_fma_f32 v[168:169], v[94:95], v[122:123], v[168:169]
	v_pk_fma_f32 v[170:171], v[96:97], v[122:123], v[170:171]
	v_pk_fma_f32 v[172:173], v[98:99], v[122:123], v[172:173]
	v_pk_fma_f32 v[174:175], v[100:101], v[122:123], v[174:175]
	v_pk_fma_f32 v[176:177], v[102:103], v[122:123], v[178:179]
	v_pk_fma_f32 v[178:179], v[104:105], v[122:123], v[180:181]
	v_pk_fma_f32 v[180:181], v[106:107], v[122:123], v[182:183]
	v_pk_fma_f32 v[182:183], v[108:109], v[122:123], v[184:185]
	v_pk_fma_f32 v[184:185], v[110:111], v[122:123], v[186:187]
	v_pk_fma_f32 v[186:187], v[112:113], v[122:123], v[188:189]
	v_pk_fma_f32 v[188:189], v[114:115], v[122:123], v[190:191]
	v_pk_fma_f32 v[190:191], v[116:117], v[122:123], v[192:193]
	v_pk_fma_f32 v[118:119], v[118:119], v[122:123], v[120:121]
	s_nop 0
	ds_read_b32 v246, v248 offset:11264
	s_waitcnt lgkmcnt(3)
	v_mov_b32_e32 v121, v247
	v_lshlrev_b32_e32 v120, 16, v121
	v_and_b32_e32 v121, 0xffff0000, v121
	v_pk_fma_f32 v[122:123], v[86:87], v[120:121], v[124:125]
	v_pk_fma_f32 v[124:125], v[88:89], v[120:121], v[128:129]
	v_pk_fma_f32 v[128:129], v[90:91], v[120:121], v[166:167]
	v_pk_fma_f32 v[166:167], v[92:93], v[120:121], v[168:169]
	v_pk_fma_f32 v[168:169], v[94:95], v[120:121], v[170:171]
	v_pk_fma_f32 v[170:171], v[96:97], v[120:121], v[172:173]
	v_pk_fma_f32 v[172:173], v[98:99], v[120:121], v[174:175]
	v_pk_fma_f32 v[174:175], v[100:101], v[120:121], v[176:177]
	v_pk_fma_f32 v[176:177], v[102:103], v[120:121], v[178:179]
	v_pk_fma_f32 v[178:179], v[104:105], v[120:121], v[180:181]
	v_pk_fma_f32 v[180:181], v[106:107], v[120:121], v[182:183]
	v_pk_fma_f32 v[182:183], v[108:109], v[120:121], v[184:185]
	v_pk_fma_f32 v[184:185], v[110:111], v[120:121], v[186:187]
	v_pk_fma_f32 v[186:187], v[112:113], v[120:121], v[188:189]
	v_pk_fma_f32 v[188:189], v[114:115], v[120:121], v[190:191]
	v_pk_fma_f32 v[116:117], v[116:117], v[120:121], v[118:119]
	s_nop 0
	ds_read_b32 v247, v248 offset:11776
	s_waitcnt lgkmcnt(3)
	v_mov_b32_e32 v119, v244
	v_lshlrev_b32_e32 v118, 16, v119
	v_and_b32_e32 v119, 0xffff0000, v119
	v_pk_fma_f32 v[120:121], v[84:85], v[118:119], v[122:123]
	v_pk_fma_f32 v[122:123], v[86:87], v[118:119], v[124:125]
	v_pk_fma_f32 v[124:125], v[88:89], v[118:119], v[128:129]
	v_pk_fma_f32 v[128:129], v[90:91], v[118:119], v[166:167]
	v_pk_fma_f32 v[166:167], v[92:93], v[118:119], v[168:169]
	v_pk_fma_f32 v[168:169], v[94:95], v[118:119], v[170:171]
	v_pk_fma_f32 v[170:171], v[96:97], v[118:119], v[172:173]
	v_pk_fma_f32 v[172:173], v[98:99], v[118:119], v[174:175]
	v_pk_fma_f32 v[174:175], v[100:101], v[118:119], v[176:177]
	v_pk_fma_f32 v[176:177], v[102:103], v[118:119], v[178:179]
	v_pk_fma_f32 v[178:179], v[104:105], v[118:119], v[180:181]
	v_pk_fma_f32 v[180:181], v[106:107], v[118:119], v[182:183]
	v_pk_fma_f32 v[182:183], v[108:109], v[118:119], v[184:185]
	v_pk_fma_f32 v[184:185], v[110:111], v[118:119], v[186:187]
	v_pk_fma_f32 v[186:187], v[112:113], v[118:119], v[188:189]
	v_pk_fma_f32 v[114:115], v[114:115], v[118:119], v[116:117]
	s_nop 0
	ds_read_b32 v244, v248 offset:12288
	s_waitcnt lgkmcnt(3)
	v_mov_b32_e32 v117, v245
	v_lshlrev_b32_e32 v116, 16, v117
	v_and_b32_e32 v117, 0xffff0000, v117
	v_pk_fma_f32 v[118:119], v[82:83], v[116:117], v[120:121]
	v_pk_fma_f32 v[120:121], v[84:85], v[116:117], v[122:123]
	v_pk_fma_f32 v[122:123], v[86:87], v[116:117], v[124:125]
	v_pk_fma_f32 v[124:125], v[88:89], v[116:117], v[128:129]
	v_pk_fma_f32 v[128:129], v[90:91], v[116:117], v[166:167]
	v_pk_fma_f32 v[166:167], v[92:93], v[116:117], v[168:169]
	v_pk_fma_f32 v[168:169], v[94:95], v[116:117], v[170:171]
	v_pk_fma_f32 v[170:171], v[96:97], v[116:117], v[172:173]
	v_pk_fma_f32 v[172:173], v[98:99], v[116:117], v[174:175]
	v_pk_fma_f32 v[174:175], v[100:101], v[116:117], v[176:177]
	v_pk_fma_f32 v[176:177], v[102:103], v[116:117], v[178:179]
	v_pk_fma_f32 v[178:179], v[104:105], v[116:117], v[180:181]
	v_pk_fma_f32 v[180:181], v[106:107], v[116:117], v[182:183]
	v_pk_fma_f32 v[182:183], v[108:109], v[116:117], v[184:185]
	v_pk_fma_f32 v[184:185], v[110:111], v[116:117], v[186:187]
	v_pk_fma_f32 v[112:113], v[112:113], v[116:117], v[114:115]
	s_nop 0
	ds_read_b32 v245, v248 offset:12800
	s_waitcnt lgkmcnt(3)
	v_mov_b32_e32 v115, v246
	v_lshlrev_b32_e32 v114, 16, v115
	v_and_b32_e32 v115, 0xffff0000, v115
	v_pk_fma_f32 v[116:117], v[80:81], v[114:115], v[118:119]
	v_pk_fma_f32 v[118:119], v[82:83], v[114:115], v[120:121]
	v_pk_fma_f32 v[120:121], v[84:85], v[114:115], v[122:123]
	v_pk_fma_f32 v[122:123], v[86:87], v[114:115], v[124:125]
	v_pk_fma_f32 v[124:125], v[88:89], v[114:115], v[128:129]
	v_pk_fma_f32 v[128:129], v[90:91], v[114:115], v[166:167]
	v_pk_fma_f32 v[166:167], v[92:93], v[114:115], v[168:169]
	v_pk_fma_f32 v[168:169], v[94:95], v[114:115], v[170:171]
	v_pk_fma_f32 v[170:171], v[96:97], v[114:115], v[172:173]
	v_pk_fma_f32 v[172:173], v[98:99], v[114:115], v[174:175]
	v_pk_fma_f32 v[174:175], v[100:101], v[114:115], v[176:177]
	v_pk_fma_f32 v[176:177], v[102:103], v[114:115], v[178:179]
	v_pk_fma_f32 v[178:179], v[104:105], v[114:115], v[180:181]
	v_pk_fma_f32 v[180:181], v[106:107], v[114:115], v[182:183]
	v_pk_fma_f32 v[182:183], v[108:109], v[114:115], v[184:185]
	v_pk_fma_f32 v[110:111], v[110:111], v[114:115], v[112:113]
	s_nop 0
	ds_read_b32 v246, v248 offset:13312
	s_waitcnt lgkmcnt(3)
	v_mov_b32_e32 v113, v247
	v_lshlrev_b32_e32 v112, 16, v113
	v_and_b32_e32 v113, 0xffff0000, v113
	v_pk_fma_f32 v[114:115], v[78:79], v[112:113], v[116:117]
	v_pk_fma_f32 v[116:117], v[80:81], v[112:113], v[118:119]
	v_pk_fma_f32 v[118:119], v[82:83], v[112:113], v[120:121]
	v_pk_fma_f32 v[120:121], v[84:85], v[112:113], v[122:123]
	v_pk_fma_f32 v[122:123], v[86:87], v[112:113], v[124:125]
	v_pk_fma_f32 v[124:125], v[88:89], v[112:113], v[128:129]
	v_pk_fma_f32 v[128:129], v[90:91], v[112:113], v[166:167]
	v_pk_fma_f32 v[166:167], v[92:93], v[112:113], v[168:169]
	v_pk_fma_f32 v[168:169], v[94:95], v[112:113], v[170:171]
	v_pk_fma_f32 v[170:171], v[96:97], v[112:113], v[172:173]
	v_pk_fma_f32 v[172:173], v[98:99], v[112:113], v[174:175]
	v_pk_fma_f32 v[174:175], v[100:101], v[112:113], v[176:177]
	v_pk_fma_f32 v[176:177], v[102:103], v[112:113], v[178:179]
	v_pk_fma_f32 v[178:179], v[104:105], v[112:113], v[180:181]
	v_pk_fma_f32 v[180:181], v[106:107], v[112:113], v[182:183]
	v_pk_fma_f32 v[108:109], v[108:109], v[112:113], v[110:111]
	s_nop 0
	ds_read_b32 v247, v248 offset:13824
	s_waitcnt lgkmcnt(3)
	v_mov_b32_e32 v111, v244
	v_lshlrev_b32_e32 v110, 16, v111
	v_and_b32_e32 v111, 0xffff0000, v111
	v_pk_fma_f32 v[112:113], v[76:77], v[110:111], v[114:115]
	v_pk_fma_f32 v[114:115], v[78:79], v[110:111], v[116:117]
	v_pk_fma_f32 v[116:117], v[80:81], v[110:111], v[118:119]
	v_pk_fma_f32 v[118:119], v[82:83], v[110:111], v[120:121]
	v_pk_fma_f32 v[120:121], v[84:85], v[110:111], v[122:123]
	v_pk_fma_f32 v[122:123], v[86:87], v[110:111], v[124:125]
	v_pk_fma_f32 v[124:125], v[88:89], v[110:111], v[128:129]
	v_pk_fma_f32 v[128:129], v[90:91], v[110:111], v[166:167]
	v_pk_fma_f32 v[166:167], v[92:93], v[110:111], v[168:169]
	v_pk_fma_f32 v[168:169], v[94:95], v[110:111], v[170:171]
	v_pk_fma_f32 v[170:171], v[96:97], v[110:111], v[172:173]
	v_pk_fma_f32 v[172:173], v[98:99], v[110:111], v[174:175]
	v_pk_fma_f32 v[174:175], v[100:101], v[110:111], v[176:177]
	v_pk_fma_f32 v[176:177], v[102:103], v[110:111], v[178:179]
	v_pk_fma_f32 v[178:179], v[104:105], v[110:111], v[180:181]
	v_pk_fma_f32 v[106:107], v[106:107], v[110:111], v[108:109]
	s_nop 0
	ds_read_b32 v244, v248 offset:14336
	s_waitcnt lgkmcnt(3)
	v_mov_b32_e32 v109, v245
	v_lshlrev_b32_e32 v108, 16, v109
	v_and_b32_e32 v109, 0xffff0000, v109
	v_pk_fma_f32 v[110:111], v[74:75], v[108:109], v[112:113]
	v_pk_fma_f32 v[112:113], v[76:77], v[108:109], v[114:115]
	v_pk_fma_f32 v[114:115], v[78:79], v[108:109], v[116:117]
	v_pk_fma_f32 v[116:117], v[80:81], v[108:109], v[118:119]
	v_pk_fma_f32 v[118:119], v[82:83], v[108:109], v[120:121]
	v_pk_fma_f32 v[120:121], v[84:85], v[108:109], v[122:123]
	v_pk_fma_f32 v[122:123], v[86:87], v[108:109], v[124:125]
	v_pk_fma_f32 v[124:125], v[88:89], v[108:109], v[128:129]
	v_pk_fma_f32 v[128:129], v[90:91], v[108:109], v[166:167]
	v_pk_fma_f32 v[166:167], v[92:93], v[108:109], v[168:169]
	v_pk_fma_f32 v[168:169], v[94:95], v[108:109], v[170:171]
	v_pk_fma_f32 v[170:171], v[96:97], v[108:109], v[172:173]
	v_pk_fma_f32 v[172:173], v[98:99], v[108:109], v[174:175]
	v_pk_fma_f32 v[174:175], v[100:101], v[108:109], v[176:177]
	v_pk_fma_f32 v[176:177], v[102:103], v[108:109], v[178:179]
	v_pk_fma_f32 v[104:105], v[104:105], v[108:109], v[106:107]
	s_nop 0
	ds_read_b32 v245, v248 offset:14848
	s_waitcnt lgkmcnt(3)
	v_mov_b32_e32 v107, v246
	v_lshlrev_b32_e32 v106, 16, v107
	v_and_b32_e32 v107, 0xffff0000, v107
	v_pk_fma_f32 v[108:109], v[72:73], v[106:107], v[110:111]
	v_pk_fma_f32 v[110:111], v[74:75], v[106:107], v[112:113]
	v_pk_fma_f32 v[112:113], v[76:77], v[106:107], v[114:115]
	v_pk_fma_f32 v[114:115], v[78:79], v[106:107], v[116:117]
	v_pk_fma_f32 v[116:117], v[80:81], v[106:107], v[118:119]
	v_pk_fma_f32 v[118:119], v[82:83], v[106:107], v[120:121]
	v_pk_fma_f32 v[120:121], v[84:85], v[106:107], v[122:123]
	v_pk_fma_f32 v[122:123], v[86:87], v[106:107], v[124:125]
	v_pk_fma_f32 v[124:125], v[88:89], v[106:107], v[128:129]
	v_pk_fma_f32 v[128:129], v[90:91], v[106:107], v[166:167]
	v_pk_fma_f32 v[166:167], v[92:93], v[106:107], v[168:169]
	v_pk_fma_f32 v[168:169], v[94:95], v[106:107], v[170:171]
	v_pk_fma_f32 v[170:171], v[96:97], v[106:107], v[172:173]
	v_pk_fma_f32 v[172:173], v[98:99], v[106:107], v[174:175]
	v_pk_fma_f32 v[174:175], v[100:101], v[106:107], v[176:177]
	v_pk_fma_f32 v[102:103], v[102:103], v[106:107], v[104:105]
	s_nop 0
	ds_read_b32 v246, v248 offset:15360
	s_waitcnt lgkmcnt(3)
	v_mov_b32_e32 v105, v247
	v_lshlrev_b32_e32 v104, 16, v105
	v_and_b32_e32 v105, 0xffff0000, v105
	v_pk_fma_f32 v[106:107], v[70:71], v[104:105], v[108:109]
	v_pk_fma_f32 v[108:109], v[72:73], v[104:105], v[110:111]
	v_pk_fma_f32 v[110:111], v[74:75], v[104:105], v[112:113]
	v_pk_fma_f32 v[112:113], v[76:77], v[104:105], v[114:115]
	v_pk_fma_f32 v[114:115], v[78:79], v[104:105], v[116:117]
	v_pk_fma_f32 v[116:117], v[80:81], v[104:105], v[118:119]
	v_pk_fma_f32 v[118:119], v[82:83], v[104:105], v[120:121]
	v_pk_fma_f32 v[120:121], v[84:85], v[104:105], v[122:123]
	v_pk_fma_f32 v[122:123], v[86:87], v[104:105], v[124:125]
	v_pk_fma_f32 v[124:125], v[88:89], v[104:105], v[128:129]
	v_pk_fma_f32 v[128:129], v[90:91], v[104:105], v[166:167]
	v_pk_fma_f32 v[166:167], v[92:93], v[104:105], v[168:169]
	v_pk_fma_f32 v[168:169], v[94:95], v[104:105], v[170:171]
	v_pk_fma_f32 v[170:171], v[96:97], v[104:105], v[172:173]
	v_pk_fma_f32 v[172:173], v[98:99], v[104:105], v[174:175]
	v_pk_fma_f32 v[100:101], v[100:101], v[104:105], v[102:103]
	s_nop 0
	ds_read_b32 v247, v248 offset:15872
	s_waitcnt lgkmcnt(3)
	v_mov_b32_e32 v103, v244
	v_lshlrev_b32_e32 v102, 16, v103
	v_and_b32_e32 v103, 0xffff0000, v103
	v_pk_fma_f32 v[104:105], v[68:69], v[102:103], v[106:107]
	v_pk_fma_f32 v[106:107], v[70:71], v[102:103], v[108:109]
	v_pk_fma_f32 v[108:109], v[72:73], v[102:103], v[110:111]
	v_pk_fma_f32 v[110:111], v[74:75], v[102:103], v[112:113]
	v_pk_fma_f32 v[112:113], v[76:77], v[102:103], v[114:115]
	v_pk_fma_f32 v[114:115], v[78:79], v[102:103], v[116:117]
	v_pk_fma_f32 v[116:117], v[80:81], v[102:103], v[118:119]
	v_pk_fma_f32 v[118:119], v[82:83], v[102:103], v[120:121]
	v_pk_fma_f32 v[120:121], v[84:85], v[102:103], v[122:123]
	v_pk_fma_f32 v[122:123], v[86:87], v[102:103], v[124:125]
	v_pk_fma_f32 v[124:125], v[88:89], v[102:103], v[128:129]
	v_pk_fma_f32 v[128:129], v[90:91], v[102:103], v[166:167]
	v_pk_fma_f32 v[166:167], v[92:93], v[102:103], v[168:169]
	v_pk_fma_f32 v[168:169], v[94:95], v[102:103], v[170:171]
	v_pk_fma_f32 v[170:171], v[96:97], v[102:103], v[172:173]
	v_pk_fma_f32 v[98:99], v[98:99], v[102:103], v[100:101]
	s_nop 0
	ds_read_b32 v244, v248 offset:16384
	s_waitcnt lgkmcnt(3)
	v_mov_b32_e32 v101, v245
	v_lshlrev_b32_e32 v100, 16, v101
	v_and_b32_e32 v101, 0xffff0000, v101
	v_pk_fma_f32 v[102:103], v[66:67], v[100:101], v[104:105]
	v_pk_fma_f32 v[104:105], v[68:69], v[100:101], v[106:107]
	v_pk_fma_f32 v[106:107], v[70:71], v[100:101], v[108:109]
	v_pk_fma_f32 v[108:109], v[72:73], v[100:101], v[110:111]
	v_pk_fma_f32 v[110:111], v[74:75], v[100:101], v[112:113]
	v_pk_fma_f32 v[112:113], v[76:77], v[100:101], v[114:115]
	v_pk_fma_f32 v[114:115], v[78:79], v[100:101], v[116:117]
	v_pk_fma_f32 v[116:117], v[80:81], v[100:101], v[118:119]
	v_pk_fma_f32 v[118:119], v[82:83], v[100:101], v[120:121]
	v_pk_fma_f32 v[120:121], v[84:85], v[100:101], v[122:123]
	v_pk_fma_f32 v[122:123], v[86:87], v[100:101], v[124:125]
	v_pk_fma_f32 v[124:125], v[88:89], v[100:101], v[128:129]
	v_pk_fma_f32 v[128:129], v[90:91], v[100:101], v[166:167]
	v_pk_fma_f32 v[166:167], v[92:93], v[100:101], v[168:169]
	v_pk_fma_f32 v[168:169], v[94:95], v[100:101], v[170:171]
	v_pk_fma_f32 v[98:99], v[96:97], v[100:101], v[98:99]
	s_nop 0
	ds_read_b32 v245, v248 offset:16896
	s_waitcnt lgkmcnt(3)
	v_mov_b32_e32 v96, v246
	v_lshlrev_b32_e32 v100, 16, v96
	v_and_b32_e32 v101, 0xffff0000, v96
	v_pk_fma_f32 v[96:97], v[64:65], v[100:101], v[102:103]
	v_pk_fma_f32 v[102:103], v[66:67], v[100:101], v[104:105]
	v_pk_fma_f32 v[104:105], v[68:69], v[100:101], v[106:107]
	v_pk_fma_f32 v[106:107], v[70:71], v[100:101], v[108:109]
	v_pk_fma_f32 v[108:109], v[72:73], v[100:101], v[110:111]
	v_pk_fma_f32 v[110:111], v[74:75], v[100:101], v[112:113]
	v_pk_fma_f32 v[112:113], v[76:77], v[100:101], v[114:115]
	v_pk_fma_f32 v[114:115], v[78:79], v[100:101], v[116:117]
	v_pk_fma_f32 v[116:117], v[80:81], v[100:101], v[118:119]
	v_pk_fma_f32 v[118:119], v[82:83], v[100:101], v[120:121]
	v_pk_fma_f32 v[120:121], v[84:85], v[100:101], v[122:123]
	v_pk_fma_f32 v[122:123], v[86:87], v[100:101], v[124:125]
	v_pk_fma_f32 v[124:125], v[88:89], v[100:101], v[128:129]
	v_pk_fma_f32 v[128:129], v[90:91], v[100:101], v[166:167]
	v_pk_fma_f32 v[166:167], v[92:93], v[100:101], v[168:169]
	v_pk_fma_f32 v[98:99], v[94:95], v[100:101], v[98:99]
	s_nop 0
	ds_read_b32 v246, v248 offset:17408
	s_waitcnt lgkmcnt(3)
	v_mov_b32_e32 v94, v247
	v_lshlrev_b32_e32 v100, 16, v94
	v_and_b32_e32 v101, 0xffff0000, v94
	v_pk_fma_f32 v[94:95], v[64:65], v[100:101], v[102:103]
	v_pk_fma_f32 v[102:103], v[66:67], v[100:101], v[104:105]
	v_pk_fma_f32 v[104:105], v[68:69], v[100:101], v[106:107]
	v_pk_fma_f32 v[106:107], v[70:71], v[100:101], v[108:109]
	v_pk_fma_f32 v[108:109], v[72:73], v[100:101], v[110:111]
	v_pk_fma_f32 v[110:111], v[74:75], v[100:101], v[112:113]
	v_pk_fma_f32 v[112:113], v[76:77], v[100:101], v[114:115]
	v_pk_fma_f32 v[114:115], v[78:79], v[100:101], v[116:117]
	v_pk_fma_f32 v[116:117], v[80:81], v[100:101], v[118:119]
	v_pk_fma_f32 v[118:119], v[82:83], v[100:101], v[120:121]
	v_pk_fma_f32 v[120:121], v[84:85], v[100:101], v[122:123]
	v_pk_fma_f32 v[122:123], v[86:87], v[100:101], v[124:125]
	v_pk_fma_f32 v[124:125], v[88:89], v[100:101], v[128:129]
	v_pk_fma_f32 v[128:129], v[90:91], v[100:101], v[166:167]
	v_pk_fma_f32 v[98:99], v[92:93], v[100:101], v[98:99]
	s_nop 0
	ds_read_b32 v247, v248 offset:17920
	s_waitcnt lgkmcnt(3)
	v_mov_b32_e32 v92, v244
	v_lshlrev_b32_e32 v100, 16, v92
	v_and_b32_e32 v101, 0xffff0000, v92
	v_pk_fma_f32 v[92:93], v[64:65], v[100:101], v[102:103]
	v_pk_fma_f32 v[102:103], v[66:67], v[100:101], v[104:105]
	v_pk_fma_f32 v[104:105], v[68:69], v[100:101], v[106:107]
	v_pk_fma_f32 v[106:107], v[70:71], v[100:101], v[108:109]
	v_pk_fma_f32 v[108:109], v[72:73], v[100:101], v[110:111]
	v_pk_fma_f32 v[110:111], v[74:75], v[100:101], v[112:113]
	v_pk_fma_f32 v[112:113], v[76:77], v[100:101], v[114:115]
	v_pk_fma_f32 v[114:115], v[78:79], v[100:101], v[116:117]
	v_pk_fma_f32 v[116:117], v[80:81], v[100:101], v[118:119]
	v_pk_fma_f32 v[118:119], v[82:83], v[100:101], v[120:121]
	v_pk_fma_f32 v[120:121], v[84:85], v[100:101], v[122:123]
	v_pk_fma_f32 v[122:123], v[86:87], v[100:101], v[124:125]
	v_pk_fma_f32 v[124:125], v[88:89], v[100:101], v[128:129]
	v_pk_fma_f32 v[98:99], v[90:91], v[100:101], v[98:99]
	s_nop 0
	ds_read_b32 v244, v248 offset:18432
	s_waitcnt lgkmcnt(3)
	v_mov_b32_e32 v90, v245
	v_lshlrev_b32_e32 v100, 16, v90
	v_and_b32_e32 v101, 0xffff0000, v90
	v_pk_fma_f32 v[90:91], v[64:65], v[100:101], v[102:103]
	v_pk_fma_f32 v[102:103], v[66:67], v[100:101], v[104:105]
	v_pk_fma_f32 v[104:105], v[68:69], v[100:101], v[106:107]
	v_pk_fma_f32 v[106:107], v[70:71], v[100:101], v[108:109]
	v_pk_fma_f32 v[108:109], v[72:73], v[100:101], v[110:111]
	v_pk_fma_f32 v[110:111], v[74:75], v[100:101], v[112:113]
	v_pk_fma_f32 v[112:113], v[76:77], v[100:101], v[114:115]
	v_pk_fma_f32 v[114:115], v[78:79], v[100:101], v[116:117]
	v_pk_fma_f32 v[116:117], v[80:81], v[100:101], v[118:119]
	v_pk_fma_f32 v[118:119], v[82:83], v[100:101], v[120:121]
	v_pk_fma_f32 v[120:121], v[84:85], v[100:101], v[122:123]
	v_pk_fma_f32 v[122:123], v[86:87], v[100:101], v[124:125]
	v_pk_fma_f32 v[98:99], v[88:89], v[100:101], v[98:99]
	s_nop 0
	ds_read_b32 v245, v248 offset:18944
	s_waitcnt lgkmcnt(3)
	v_mov_b32_e32 v88, v246
	v_lshlrev_b32_e32 v100, 16, v88
	v_and_b32_e32 v101, 0xffff0000, v88
	v_pk_fma_f32 v[88:89], v[64:65], v[100:101], v[102:103]
	v_pk_fma_f32 v[102:103], v[66:67], v[100:101], v[104:105]
	v_pk_fma_f32 v[104:105], v[68:69], v[100:101], v[106:107]
	v_pk_fma_f32 v[106:107], v[70:71], v[100:101], v[108:109]
	v_pk_fma_f32 v[108:109], v[72:73], v[100:101], v[110:111]
	v_pk_fma_f32 v[110:111], v[74:75], v[100:101], v[112:113]
	v_pk_fma_f32 v[112:113], v[76:77], v[100:101], v[114:115]
	v_pk_fma_f32 v[114:115], v[78:79], v[100:101], v[116:117]
	v_pk_fma_f32 v[116:117], v[80:81], v[100:101], v[118:119]
	v_pk_fma_f32 v[118:119], v[82:83], v[100:101], v[120:121]
	v_pk_fma_f32 v[120:121], v[84:85], v[100:101], v[122:123]
	v_pk_fma_f32 v[98:99], v[86:87], v[100:101], v[98:99]
	s_nop 0
	ds_read_b32 v246, v248 offset:19456
	s_waitcnt lgkmcnt(3)
	v_mov_b32_e32 v86, v247
	v_lshlrev_b32_e32 v100, 16, v86
	v_and_b32_e32 v101, 0xffff0000, v86
	v_pk_fma_f32 v[86:87], v[64:65], v[100:101], v[102:103]
	v_pk_fma_f32 v[102:103], v[66:67], v[100:101], v[104:105]
	v_pk_fma_f32 v[104:105], v[68:69], v[100:101], v[106:107]
	v_pk_fma_f32 v[106:107], v[70:71], v[100:101], v[108:109]
	v_pk_fma_f32 v[108:109], v[72:73], v[100:101], v[110:111]
	v_pk_fma_f32 v[110:111], v[74:75], v[100:101], v[112:113]
	v_pk_fma_f32 v[112:113], v[76:77], v[100:101], v[114:115]
	v_pk_fma_f32 v[114:115], v[78:79], v[100:101], v[116:117]
	v_pk_fma_f32 v[116:117], v[80:81], v[100:101], v[118:119]
	v_pk_fma_f32 v[118:119], v[82:83], v[100:101], v[120:121]
	v_pk_fma_f32 v[98:99], v[84:85], v[100:101], v[98:99]
	s_nop 0
	ds_read_b32 v247, v248 offset:19968
	s_waitcnt lgkmcnt(3)
	v_mov_b32_e32 v84, v244
	v_lshlrev_b32_e32 v100, 16, v84
	v_and_b32_e32 v101, 0xffff0000, v84
	v_pk_fma_f32 v[84:85], v[64:65], v[100:101], v[102:103]
	v_pk_fma_f32 v[102:103], v[66:67], v[100:101], v[104:105]
	v_pk_fma_f32 v[104:105], v[68:69], v[100:101], v[106:107]
	v_pk_fma_f32 v[106:107], v[70:71], v[100:101], v[108:109]
	v_pk_fma_f32 v[108:109], v[72:73], v[100:101], v[110:111]
	v_pk_fma_f32 v[110:111], v[74:75], v[100:101], v[112:113]
	v_pk_fma_f32 v[112:113], v[76:77], v[100:101], v[114:115]
	v_pk_fma_f32 v[114:115], v[78:79], v[100:101], v[116:117]
	v_pk_fma_f32 v[116:117], v[80:81], v[100:101], v[118:119]
	v_pk_fma_f32 v[98:99], v[82:83], v[100:101], v[98:99]
	s_nop 0
	ds_read_b32 v244, v248 offset:20480
	s_waitcnt lgkmcnt(3)
	v_mov_b32_e32 v82, v245
	v_lshlrev_b32_e32 v100, 16, v82
	v_and_b32_e32 v101, 0xffff0000, v82
	v_pk_fma_f32 v[82:83], v[64:65], v[100:101], v[102:103]
	v_pk_fma_f32 v[102:103], v[66:67], v[100:101], v[104:105]
	v_pk_fma_f32 v[104:105], v[68:69], v[100:101], v[106:107]
	v_pk_fma_f32 v[106:107], v[70:71], v[100:101], v[108:109]
	v_pk_fma_f32 v[108:109], v[72:73], v[100:101], v[110:111]
	v_pk_fma_f32 v[110:111], v[74:75], v[100:101], v[112:113]
	v_pk_fma_f32 v[112:113], v[76:77], v[100:101], v[114:115]
	v_pk_fma_f32 v[114:115], v[78:79], v[100:101], v[116:117]
	v_pk_fma_f32 v[98:99], v[80:81], v[100:101], v[98:99]
	s_nop 0
	ds_read_b32 v245, v248 offset:20992
	s_waitcnt lgkmcnt(3)
	v_mov_b32_e32 v80, v246
	v_lshlrev_b32_e32 v100, 16, v80
	v_and_b32_e32 v101, 0xffff0000, v80
	v_pk_fma_f32 v[80:81], v[64:65], v[100:101], v[102:103]
	v_pk_fma_f32 v[102:103], v[66:67], v[100:101], v[104:105]
	v_pk_fma_f32 v[104:105], v[68:69], v[100:101], v[106:107]
	v_pk_fma_f32 v[106:107], v[70:71], v[100:101], v[108:109]
	v_pk_fma_f32 v[108:109], v[72:73], v[100:101], v[110:111]
	v_pk_fma_f32 v[110:111], v[74:75], v[100:101], v[112:113]
	v_pk_fma_f32 v[112:113], v[76:77], v[100:101], v[114:115]
	v_pk_fma_f32 v[98:99], v[78:79], v[100:101], v[98:99]
	s_nop 0
	ds_read_b32 v246, v248 offset:21504
	s_waitcnt lgkmcnt(3)
	v_mov_b32_e32 v78, v247
	v_lshlrev_b32_e32 v100, 16, v78
	v_and_b32_e32 v101, 0xffff0000, v78
	v_pk_fma_f32 v[78:79], v[64:65], v[100:101], v[102:103]
	v_pk_fma_f32 v[102:103], v[66:67], v[100:101], v[104:105]
	v_pk_fma_f32 v[104:105], v[68:69], v[100:101], v[106:107]
	v_pk_fma_f32 v[106:107], v[70:71], v[100:101], v[108:109]
	v_pk_fma_f32 v[108:109], v[72:73], v[100:101], v[110:111]
	v_pk_fma_f32 v[110:111], v[74:75], v[100:101], v[112:113]
	v_pk_fma_f32 v[76:77], v[76:77], v[100:101], v[98:99]
	s_nop 0
	ds_read_b32 v247, v248 offset:22016
	s_waitcnt lgkmcnt(3)
	v_mov_b32_e32 v99, v244
	v_lshlrev_b32_e32 v98, 16, v99
	v_and_b32_e32 v99, 0xffff0000, v99
	v_pk_fma_f32 v[100:101], v[64:65], v[98:99], v[102:103]
	v_pk_fma_f32 v[102:103], v[66:67], v[98:99], v[104:105]
	v_pk_fma_f32 v[104:105], v[68:69], v[98:99], v[106:107]
	v_pk_fma_f32 v[106:107], v[70:71], v[98:99], v[108:109]
	v_pk_fma_f32 v[108:109], v[72:73], v[98:99], v[110:111]
	v_pk_fma_f32 v[74:75], v[74:75], v[98:99], v[76:77]
	v_and_b32_e32 v110, 63, v156
	ds_read_b32 v244, v248 offset:22528
	s_waitcnt lgkmcnt(3)
	v_mov_b32_e32 v77, v245
	v_lshlrev_b32_e32 v76, 16, v77
	v_and_b32_e32 v77, 0xffff0000, v77
	v_pk_fma_f32 v[98:99], v[64:65], v[76:77], v[102:103]
	v_pk_fma_f32 v[102:103], v[66:67], v[76:77], v[104:105]
	v_pk_fma_f32 v[104:105], v[68:69], v[76:77], v[106:107]
	v_pk_fma_f32 v[106:107], v[70:71], v[76:77], v[108:109]
	v_pk_fma_f32 v[72:73], v[72:73], v[76:77], v[74:75]
	s_nop 0
	ds_read_b32 v245, v248 offset:23040
	s_waitcnt lgkmcnt(3)
	v_mov_b32_e32 v75, v246
	v_lshlrev_b32_e32 v74, 16, v75
	v_and_b32_e32 v75, 0xffff0000, v75
	v_pk_fma_f32 v[76:77], v[64:65], v[74:75], v[102:103]
	v_pk_fma_f32 v[102:103], v[66:67], v[74:75], v[104:105]
	v_pk_fma_f32 v[104:105], v[68:69], v[74:75], v[106:107]
	v_pk_fma_f32 v[70:71], v[70:71], v[74:75], v[72:73]
	s_nop 0
	s_waitcnt lgkmcnt(2)
	v_mov_b32_e32 v73, v247
	v_lshlrev_b32_e32 v72, 16, v73
	v_and_b32_e32 v73, 0xffff0000, v73
	v_pk_fma_f32 v[74:75], v[64:65], v[72:73], v[102:103]
	v_pk_fma_f32 v[102:103], v[66:67], v[72:73], v[104:105]
	v_pk_fma_f32 v[68:69], v[68:69], v[72:73], v[70:71]
	s_nop 0
	s_waitcnt lgkmcnt(1)
	v_mov_b32_e32 v71, v244
	v_lshlrev_b32_e32 v70, 16, v71
	v_and_b32_e32 v71, 0xffff0000, v71
	v_pk_fma_f32 v[72:73], v[64:65], v[70:71], v[102:103]
	v_pk_fma_f32 v[66:67], v[66:67], v[70:71], v[68:69]
	s_nop 0
	s_waitcnt lgkmcnt(0)
	v_mov_b32_e32 v69, v245
	v_lshlrev_b32_e32 v68, 16, v69
	v_and_b32_e32 v69, 0xffff0000, v69
	v_pk_fma_f32 v[64:65], v[64:65], v[68:69], v[66:67]
	v_lshl_add_u32 v66, v157, 3, 0
	v_lshl_add_u32 v67, v159, 10, v66
	ds_write_b64 v67, v[96:97] offset:48128
	v_lshl_add_u32 v67, v160, 10, v66
	ds_write_b64 v67, v[94:95] offset:48128
	v_lshl_add_u32 v67, v126, 10, v66
	ds_write_b64 v67, v[92:93] offset:48128
	v_lshl_add_u32 v67, v127, 10, v66
	ds_write_b64 v67, v[90:91] offset:48128
	v_lshl_add_u32 v67, v162, 10, v66
	ds_write_b64 v67, v[88:89] offset:48128
	v_lshl_add_u32 v67, v163, 10, v66
	ds_write_b64 v67, v[86:87] offset:48128
	v_lshl_add_u32 v67, v164, 10, v66
	ds_write_b64 v67, v[84:85] offset:48128
	v_lshl_add_u32 v67, v165, 10, v66
	ds_write_b64 v67, v[82:83] offset:48128
	v_lshl_add_u32 v67, v144, 10, v66
	ds_write_b64 v67, v[80:81] offset:48128
	v_lshl_add_u32 v67, v142, 10, v66
	ds_write_b64 v67, v[78:79] offset:48128
	v_lshl_add_u32 v67, v140, 10, v66
	ds_write_b64 v67, v[100:101] offset:48128
	v_lshl_add_u32 v67, v138, 10, v66
	ds_write_b64 v67, v[98:99] offset:48128
	v_lshl_add_u32 v67, v136, 10, v66
	ds_write_b64 v67, v[76:77] offset:48128
	v_lshl_add_u32 v67, v134, 10, v66
	ds_write_b64 v67, v[74:75] offset:48128
	v_lshl_add_u32 v67, v132, 10, v66
	v_lshl_add_u32 v66, v130, 10, v66
	v_lshlrev_b32_e32 v68, 4, v110
	ds_write_b64 v67, v[72:73] offset:48128
	ds_write_b64 v66, v[64:65] offset:48128
	s_waitcnt lgkmcnt(0)
	s_barrier
	global_load_dwordx4 v[64:67], v68, s[42:43]
	v_readlane_b32 s42, v255, 7
	v_readlane_b32 s43, v255, 8
	v_add_u32_e32 v106, s23, v68
	ds_read_b128 v[100:103], v106 offset:48128
	ds_read_b128 v[96:99], v106 offset:49152
	ds_read_b128 v[92:95], v106 offset:50176
	ds_read_b128 v[88:91], v106 offset:51200
	global_load_dwordx4 v[68:71], v68, s[42:43]
	s_waitcnt lgkmcnt(3)
	v_mov_b32_e32 v72, v101
	v_mov_b32_e32 v73, v102
	v_mov_b32_e32 v74, v100
	v_mov_b32_e32 v75, v103
	v_pk_add_f32 v[72:73], v[72:73], v[74:75]
	v_pk_mul_f32 v[74:75], v[100:101], v[100:101]
	v_add_f32_e32 v111, v72, v73
	v_pk_mul_f32 v[72:73], v[102:103], v[102:103]
	ds_read_b128 v[84:87], v106 offset:52224
	ds_read_b128 v[80:83], v106 offset:53248
	v_pk_mov_b32 v[76:77], v[74:75], v[72:73] op_sel:[1,0]
	v_mov_b32_e32 v75, v73
	v_pk_add_f32 v[72:73], v[76:77], v[74:75]
	s_waitcnt lgkmcnt(4)
	v_mov_b32_e32 v74, v96
	v_add_f32_e32 v112, v72, v73
	v_mov_b32_e32 v72, v97
	v_mov_b32_e32 v73, v98
	v_mov_b32_e32 v75, v99
	v_pk_add_f32 v[72:73], v[72:73], v[74:75]
	v_pk_mul_f32 v[74:75], v[96:97], v[96:97]
	v_add_f32_e32 v113, v72, v73
	v_pk_mul_f32 v[72:73], v[98:99], v[98:99]
	s_nop 0
	v_pk_mov_b32 v[76:77], v[74:75], v[72:73] op_sel:[1,0]
	v_mov_b32_e32 v75, v73
	v_pk_add_f32 v[72:73], v[76:77], v[74:75]
	s_waitcnt lgkmcnt(3)
	v_mov_b32_e32 v74, v92
	v_add_f32_e32 v114, v72, v73
	v_mov_b32_e32 v72, v93
	v_mov_b32_e32 v73, v94
	v_mov_b32_e32 v75, v95
	v_pk_add_f32 v[72:73], v[72:73], v[74:75]
	v_pk_mul_f32 v[74:75], v[92:93], v[92:93]
	v_add_f32_e32 v115, v72, v73
	v_pk_mul_f32 v[72:73], v[94:95], v[94:95]
	s_nop 0
	v_pk_mov_b32 v[76:77], v[74:75], v[72:73] op_sel:[1,0]
	v_mov_b32_e32 v75, v73
	v_pk_add_f32 v[72:73], v[76:77], v[74:75]
	s_waitcnt lgkmcnt(2)
	v_mov_b32_e32 v74, v88
	v_add_f32_e32 v116, v72, v73
	v_mov_b32_e32 v72, v89
	v_mov_b32_e32 v73, v90
	v_mov_b32_e32 v75, v91
	v_pk_add_f32 v[72:73], v[72:73], v[74:75]
	v_pk_mul_f32 v[74:75], v[88:89], v[88:89]
	v_add_f32_e32 v117, v72, v73
	v_pk_mul_f32 v[72:73], v[90:91], v[90:91]
	s_nop 0
	v_pk_mov_b32 v[76:77], v[74:75], v[72:73] op_sel:[1,0]
	v_mov_b32_e32 v75, v73
	v_pk_add_f32 v[72:73], v[76:77], v[74:75]
	s_waitcnt lgkmcnt(1)
	v_mov_b32_e32 v74, v84
	v_add_f32_e32 v118, v72, v73
	v_mov_b32_e32 v72, v85
	v_mov_b32_e32 v73, v86
	v_mov_b32_e32 v75, v87
	v_pk_add_f32 v[72:73], v[72:73], v[74:75]
	v_pk_mul_f32 v[74:75], v[84:85], v[84:85]
	v_add_f32_e32 v119, v72, v73
	v_pk_mul_f32 v[72:73], v[86:87], v[86:87]
	s_nop 0
	v_pk_mov_b32 v[76:77], v[74:75], v[72:73] op_sel:[1,0]
	v_mov_b32_e32 v75, v73
	v_pk_add_f32 v[72:73], v[76:77], v[74:75]
	s_waitcnt lgkmcnt(0)
	v_mov_b32_e32 v74, v80
	v_add_f32_e32 v120, v72, v73
	v_mov_b32_e32 v72, v81
	v_mov_b32_e32 v73, v82
	v_mov_b32_e32 v75, v83
	ds_read_b128 v[76:79], v106 offset:54272
	v_pk_add_f32 v[72:73], v[72:73], v[74:75]
	v_pk_mul_f32 v[74:75], v[80:81], v[80:81]
	v_add_f32_e32 v121, v72, v73
	v_pk_mul_f32 v[72:73], v[82:83], v[82:83]
	s_nop 0
	v_pk_mov_b32 v[104:105], v[74:75], v[72:73] op_sel:[1,0]
	v_mov_b32_e32 v75, v73
	v_pk_add_f32 v[72:73], v[104:105], v[74:75]
	s_nop 0
	v_add_f32_e32 v122, v72, v73
	ds_read_b128 v[72:75], v106 offset:55296
	s_waitcnt lgkmcnt(1)
	v_mov_b32_e32 v104, v77
	v_mov_b32_e32 v105, v78
	v_mov_b32_e32 v106, v76
	v_mov_b32_e32 v107, v79
	v_pk_add_f32 v[104:105], v[104:105], v[106:107]
	v_pk_mul_f32 v[106:107], v[76:77], v[76:77]
	v_add_f32_e32 v123, v104, v105
	v_pk_mul_f32 v[104:105], v[78:79], v[78:79]
	s_nop 0
	v_pk_mov_b32 v[108:109], v[106:107], v[104:105] op_sel:[1,0]
	v_mov_b32_e32 v107, v105
	v_pk_add_f32 v[104:105], v[108:109], v[106:107]
	s_waitcnt lgkmcnt(0)
	v_mov_b32_e32 v106, v72
	v_add_f32_e32 v124, v104, v105
	v_mov_b32_e32 v104, v73
	v_mov_b32_e32 v105, v74
	v_mov_b32_e32 v107, v75
	v_pk_add_f32 v[104:105], v[104:105], v[106:107]
	v_pk_mul_f32 v[106:107], v[72:73], v[72:73]
	v_add_f32_e32 v125, v104, v105
	v_pk_mul_f32 v[104:105], v[74:75], v[74:75]
	s_nop 0
	v_pk_mov_b32 v[108:109], v[106:107], v[104:105] op_sel:[1,0]
	v_mov_b32_e32 v107, v105
	v_pk_add_f32 v[104:105], v[108:109], v[106:107]
	v_add_f32_dpp v106, v112, v112 quad_perm:[1,0,3,2] row_mask:0xf bank_mask:0xf bound_ctrl:1
	v_add_f32_e32 v104, v104, v105
	v_add_f32_dpp v105, v111, v111 quad_perm:[1,0,3,2] row_mask:0xf bank_mask:0xf bound_ctrl:1
	v_add_f32_dpp v111, v116, v116 quad_perm:[1,0,3,2] row_mask:0xf bank_mask:0xf bound_ctrl:1
	v_add_f32_dpp v104, v104, v104 quad_perm:[1,0,3,2] row_mask:0xf bank_mask:0xf bound_ctrl:1
	v_add_f32_dpp v105, v105, v105 quad_perm:[2,3,0,1] row_mask:0xf bank_mask:0xf bound_ctrl:1
	v_add_f32_dpp v116, v121, v121 quad_perm:[1,0,3,2] row_mask:0xf bank_mask:0xf bound_ctrl:1
	v_add_f32_dpp v104, v104, v104 quad_perm:[2,3,0,1] row_mask:0xf bank_mask:0xf bound_ctrl:1
	v_add_f32_dpp v105, v105, v105 row_half_mirror row_mask:0xf bank_mask:0xf bound_ctrl:1
	v_add_f32_dpp v106, v106, v106 quad_perm:[2,3,0,1] row_mask:0xf bank_mask:0xf bound_ctrl:1
	v_add_f32_dpp v121, v104, v104 row_half_mirror row_mask:0xf bank_mask:0xf bound_ctrl:1
	v_add_f32_dpp v104, v105, v105 row_mirror row_mask:0xf bank_mask:0xf bound_ctrl:1
	v_add_f32_dpp v106, v106, v106 row_half_mirror row_mask:0xf bank_mask:0xf bound_ctrl:1
	v_readlane_b32 s23, v104, 16
	v_readlane_b32 s44, v104, 48
	v_add_f32_dpp v107, v113, v113 quad_perm:[1,0,3,2] row_mask:0xf bank_mask:0xf bound_ctrl:1
	v_add_f32_dpp v112, v117, v117 quad_perm:[1,0,3,2] row_mask:0xf bank_mask:0xf bound_ctrl:1
	v_add_f32_dpp v117, v122, v122 quad_perm:[1,0,3,2] row_mask:0xf bank_mask:0xf bound_ctrl:1
	v_add_f32_dpp v122, v106, v106 row_mirror row_mask:0xf bank_mask:0xf bound_ctrl:1
	v_readlane_b32 s42, v104, 0
	v_readlane_b32 s43, v104, 32
	v_mov_b32_e32 v104, s23
	v_mov_b32_e32 v105, s44
	v_add_f32_dpp v108, v114, v114 quad_perm:[1,0,3,2] row_mask:0xf bank_mask:0xf bound_ctrl:1
	v_add_f32_dpp v109, v115, v115 quad_perm:[1,0,3,2] row_mask:0xf bank_mask:0xf bound_ctrl:1
	v_add_f32_dpp v107, v107, v107 quad_perm:[2,3,0,1] row_mask:0xf bank_mask:0xf bound_ctrl:1
	v_pk_add_f32 v[104:105], s[42:43], v[104:105]
	v_readlane_b32 s42, v122, 16
	v_add_f32_dpp v108, v108, v108 quad_perm:[2,3,0,1] row_mask:0xf bank_mask:0xf bound_ctrl:1
	v_add_f32_dpp v109, v109, v109 quad_perm:[2,3,0,1] row_mask:0xf bank_mask:0xf bound_ctrl:1
	v_add_f32_dpp v107, v107, v107 row_half_mirror row_mask:0xf bank_mask:0xf bound_ctrl:1
	v_readlane_b32 s23, v122, 0
	v_mov_b32_e32 v106, s42
	v_readlane_b32 s42, v122, 48
	v_add_f32_dpp v113, v118, v118 quad_perm:[1,0,3,2] row_mask:0xf bank_mask:0xf bound_ctrl:1
	v_add_f32_dpp v118, v123, v123 quad_perm:[1,0,3,2] row_mask:0xf bank_mask:0xf bound_ctrl:1
	v_add_f32_dpp v108, v108, v108 row_half_mirror row_mask:0xf bank_mask:0xf bound_ctrl:1
	v_add_f32_dpp v109, v109, v109 row_half_mirror row_mask:0xf bank_mask:0xf bound_ctrl:1
	v_add_f32_dpp v123, v107, v107 row_mirror row_mask:0xf bank_mask:0xf bound_ctrl:1
	v_add_f32_e32 v106, s23, v106
	v_readlane_b32 s23, v122, 32
	v_mov_b32_e32 v107, s42
	v_add_f32_dpp v114, v119, v119 quad_perm:[1,0,3,2] row_mask:0xf bank_mask:0xf bound_ctrl:1
	v_add_f32_dpp v115, v120, v120 quad_perm:[1,0,3,2] row_mask:0xf bank_mask:0xf bound_ctrl:1
	v_add_f32_dpp v119, v124, v124 quad_perm:[1,0,3,2] row_mask:0xf bank_mask:0xf bound_ctrl:1
	v_add_f32_dpp v120, v125, v125 quad_perm:[1,0,3,2] row_mask:0xf bank_mask:0xf bound_ctrl:1
	v_add_f32_dpp v124, v108, v108 row_mirror row_mask:0xf bank_mask:0xf bound_ctrl:1
	v_add_f32_dpp v125, v109, v109 row_mirror row_mask:0xf bank_mask:0xf bound_ctrl:1
	v_add_f32_e32 v108, s23, v107
	v_mov_b32_e32 v107, v104
	v_mov_b32_e32 v109, v105
	v_pk_add_f32 v[104:105], v[106:107], v[108:109]
	v_readlane_b32 s23, v123, 16
	v_pk_mul_f32 v[104:105], v[104:105], s[46:47] op_sel_hi:[1,0]
	v_readlane_b32 s44, v123, 48
	v_fma_f32 v106, -v105, v105, v104
	v_max_f32_e32 v106, 0, v106
	v_add_f32_e32 v106, 0x3727c5ac, v106
	v_rsq_f32_e32 v106, v106
	v_pk_add_f32 v[100:101], v[100:101], v[104:105] op_sel:[0,1] neg_lo:[0,1] neg_hi:[0,1]
	v_pk_add_f32 v[102:103], v[102:103], v[104:105] op_sel:[0,1] neg_lo:[0,1] neg_hi:[0,1]
	v_readlane_b32 s42, v123, 0
	v_pk_mul_f32 v[100:101], v[100:101], v[106:107] op_sel_hi:[1,0]
	v_readlane_b32 s43, v123, 32
	s_waitcnt vmcnt(0)
	s_cmp_lg_u32 s40, 0
	s_cbranch_scc1 .Lep_skip
	global_load_dword v250, v149, s[28:29] sc1
.Lep_skip:
	v_pk_fma_f32 v[100:101], v[64:65], v[100:101], v[68:69]
	v_add_f32_dpp v111, v111, v111 quad_perm:[2,3,0,1] row_mask:0xf bank_mask:0xf bound_ctrl:1
	v_mul_f32_e32 v107, 0xbfb8aa3b, v100
	v_exp_f32_e32 v107, v107
	v_mul_f32_e32 v108, 0xbfb8aa3b, v101
	v_exp_f32_e32 v109, v108
	v_add_f32_dpp v111, v111, v111 row_half_mirror row_mask:0xf bank_mask:0xf bound_ctrl:1
	v_add_f32_e32 v107, 1.0, v107
	v_rcp_f32_e32 v108, v107
	v_add_f32_e32 v107, 1.0, v109
	v_pk_mul_f32 v[102:103], v[102:103], v[106:107] op_sel_hi:[1,0]
	v_rcp_f32_e32 v109, v107
	v_pk_fma_f32 v[102:103], v[66:67], v[102:103], v[70:71]
	v_add_f32_dpp v111, v111, v111 row_mirror row_mask:0xf bank_mask:0xf bound_ctrl:1
	v_mul_f32_e32 v104, 0xbfb8aa3b, v102
	v_mul_f32_e32 v105, 0xbfb8aa3b, v103
	v_exp_f32_e32 v104, v104
	v_exp_f32_e32 v105, v105
	v_pk_mul_f32 v[100:101], v[100:101], v[108:109]
	v_add_f32_dpp v112, v112, v112 quad_perm:[2,3,0,1] row_mask:0xf bank_mask:0xf bound_ctrl:1
	v_add_f32_e32 v104, 1.0, v104
	v_add_f32_e32 v105, 1.0, v105
	v_rcp_f32_e32 v104, v104
	v_rcp_f32_e32 v105, v105
	v_cvt_pk_bf16_f32 v100, v100, v101
	v_add_f32_dpp v113, v113, v113 quad_perm:[2,3,0,1] row_mask:0xf bank_mask:0xf bound_ctrl:1
	v_add_f32_dpp v112, v112, v112 row_half_mirror row_mask:0xf bank_mask:0xf bound_ctrl:1
	v_pk_mul_f32 v[102:103], v[102:103], v[104:105]
	v_add_f32_dpp v113, v113, v113 row_half_mirror row_mask:0xf bank_mask:0xf bound_ctrl:1
	v_cvt_pk_bf16_f32 v101, v102, v103
	v_mov_b32_e32 v102, s23
	v_mov_b32_e32 v103, s44
	v_pk_add_f32 v[102:103], s[42:43], v[102:103]
	v_readlane_b32 s42, v124, 16
	v_readlane_b32 s23, v124, 0
	v_mov_b32_e32 v107, v103
	v_mov_b32_e32 v104, s42
	v_readlane_b32 s42, v124, 48
	v_add_f32_e32 v104, s23, v104
	v_readlane_b32 s23, v124, 32
	v_mov_b32_e32 v105, s42
	v_readlane_b32 s42, v125, 0
	v_add_f32_e32 v106, s23, v105
	v_mov_b32_e32 v105, v102
	v_pk_add_f32 v[102:103], v[104:105], v[106:107]
	s_mul_i32 s23, s27, 0x1080
	v_pk_mul_f32 v[102:103], v[102:103], s[46:47] op_sel_hi:[1,0]
	s_add_i32 s23, s23, 0
	v_fma_f32 v104, -v103, v103, v102
	v_max_f32_e32 v104, 0, v104
	v_add_f32_e32 v104, 0x3727c5ac, v104
	v_rsq_f32_e32 v104, v104
	v_pk_add_f32 v[96:97], v[96:97], v[102:103] op_sel:[0,1] neg_lo:[0,1] neg_hi:[0,1]
	v_pk_add_f32 v[98:99], v[98:99], v[102:103] op_sel:[0,1] neg_lo:[0,1] neg_hi:[0,1]
	v_readlane_b32 s27, v125, 48
	v_pk_mul_f32 v[96:97], v[96:97], v[104:105] op_sel_hi:[1,0]
	v_lshl_add_u32 v122, v110, 3, s23
	v_pk_fma_f32 v[96:97], v[64:65], v[96:97], v[68:69]
	v_readlane_b32 s23, v125, 16
	v_mul_f32_e32 v105, 0xbfb8aa3b, v96
	v_exp_f32_e32 v105, v105
	v_mul_f32_e32 v106, 0xbfb8aa3b, v97
	v_exp_f32_e32 v107, v106
	v_readlane_b32 s43, v125, 32
	v_add_f32_e32 v105, 1.0, v105
	v_rcp_f32_e32 v106, v105
	v_add_f32_e32 v105, 1.0, v107
	v_pk_mul_f32 v[98:99], v[98:99], v[104:105] op_sel_hi:[1,0]
	v_rcp_f32_e32 v107, v105
	v_mov_b32_e32 v105, s27
	v_readlane_b32 s27, v111, 16
	v_mov_b32_e32 v104, s23
	v_readlane_b32 s23, v111, 0
	v_mov_b32_e32 v108, s27
	v_readlane_b32 s27, v111, 48
	v_pk_add_f32 v[104:105], s[42:43], v[104:105]
	v_add_f32_e32 v108, s23, v108
	v_readlane_b32 s23, v111, 32
	v_mov_b32_e32 v109, s27
	v_mov_b32_e32 v111, v105
	v_add_f32_e32 v110, s23, v109
	v_mov_b32_e32 v109, v104
	v_pk_fma_f32 v[98:99], v[66:67], v[98:99], v[70:71]
	v_pk_add_f32 v[104:105], v[108:109], v[110:111]
	v_mul_f32_e32 v102, 0xbfb8aa3b, v98
	v_mul_f32_e32 v103, 0xbfb8aa3b, v99
	v_pk_mul_f32 v[104:105], v[104:105], s[46:47] op_sel_hi:[1,0]
	v_exp_f32_e32 v102, v102
	v_exp_f32_e32 v103, v103
	v_fma_f32 v108, -v105, v105, v104
	v_max_f32_e32 v108, 0, v108
	v_add_f32_e32 v108, 0x3727c5ac, v108
	v_rsq_f32_e32 v108, v108
	v_add_f32_e32 v102, 1.0, v102
	v_add_f32_e32 v103, 1.0, v103
	v_rcp_f32_e32 v102, v102
	v_rcp_f32_e32 v103, v103
	v_pk_add_f32 v[92:93], v[92:93], v[104:105] op_sel:[0,1] neg_lo:[0,1] neg_hi:[0,1]
	v_pk_mul_f32 v[96:97], v[96:97], v[106:107]
	v_pk_mul_f32 v[92:93], v[92:93], v[108:109] op_sel_hi:[1,0]
	v_pk_mul_f32 v[98:99], v[98:99], v[102:103]
	v_pk_fma_f32 v[92:93], v[64:65], v[92:93], v[68:69]
	v_pk_add_f32 v[94:95], v[94:95], v[104:105] op_sel:[0,1] neg_lo:[0,1] neg_hi:[0,1]
	v_mul_f32_e32 v102, 0xbfb8aa3b, v92
	v_exp_f32_e32 v102, v102
	v_mul_f32_e32 v103, 0xbfb8aa3b, v93
	v_exp_f32_e32 v103, v103
	v_cvt_pk_bf16_f32 v96, v96, v97
	v_add_f32_e32 v97, 1.0, v102
	v_pk_mul_f32 v[94:95], v[94:95], v[108:109] op_sel_hi:[1,0]
	v_add_f32_dpp v112, v112, v112 row_mirror row_mask:0xf bank_mask:0xf bound_ctrl:1
	v_rcp_f32_e32 v102, v97
	v_add_f32_e32 v97, 1.0, v103
	v_pk_fma_f32 v[94:95], v[66:67], v[94:95], v[70:71]
	v_add_f32_dpp v113, v113, v113 row_mirror row_mask:0xf bank_mask:0xf bound_ctrl:1
	v_rcp_f32_e32 v103, v97
	v_mul_f32_e32 v97, 0xbfb8aa3b, v94
	v_readlane_b32 s27, v112, 48
	v_exp_f32_e32 v104, v97
	v_cvt_pk_bf16_f32 v97, v98, v99
	v_readlane_b32 s23, v112, 16
	v_mov_b32_e32 v99, s27
	v_readlane_b32 s27, v113, 16
	ds_write2_b64 v122, v[100:101], v[96:97] offset1:66
	v_readlane_b32 s42, v112, 0
	v_readlane_b32 s43, v112, 32
	v_mov_b32_e32 v98, s23
	v_readlane_b32 s23, v113, 0
	v_mov_b32_e32 v100, s27
	v_readlane_b32 s27, v113, 48
	v_pk_add_f32 v[98:99], s[42:43], v[98:99]
	v_add_f32_e32 v100, s23, v100
	v_readlane_b32 s23, v113, 32
	v_mov_b32_e32 v101, s27
	v_pk_mul_f32 v[92:93], v[92:93], v[102:103]
	v_add_f32_e32 v102, s23, v101
	v_mov_b32_e32 v101, v98
	v_mov_b32_e32 v103, v99
	v_pk_add_f32 v[98:99], v[100:101], v[102:103]
	v_mul_f32_e32 v97, 0xbfb8aa3b, v95
	v_pk_mul_f32 v[98:99], v[98:99], s[46:47] op_sel_hi:[1,0]
	v_exp_f32_e32 v97, v97
	v_fma_f32 v100, -v99, v99, v98
	v_max_f32_e32 v100, 0, v100
	v_add_f32_e32 v100, 0x3727c5ac, v100
	v_rsq_f32_e32 v100, v100
	v_pk_add_f32 v[88:89], v[88:89], v[98:99] op_sel:[0,1] neg_lo:[0,1] neg_hi:[0,1]
	v_pk_add_f32 v[90:91], v[90:91], v[98:99] op_sel:[0,1] neg_lo:[0,1] neg_hi:[0,1]
	v_add_f32_e32 v96, 1.0, v104
	v_pk_mul_f32 v[88:89], v[88:89], v[100:101] op_sel_hi:[1,0]
	v_add_f32_e32 v97, 1.0, v97
	v_pk_fma_f32 v[88:89], v[64:65], v[88:89], v[68:69]
	v_rcp_f32_e32 v96, v96
	v_mul_f32_e32 v101, 0xbfb8aa3b, v88
	v_exp_f32_e32 v101, v101
	v_mul_f32_e32 v102, 0xbfb8aa3b, v89
	v_rcp_f32_e32 v97, v97
	v_exp_f32_e32 v102, v102
	v_pk_mul_f32 v[90:91], v[90:91], v[100:101] op_sel_hi:[1,0]
	v_add_f32_dpp v114, v114, v114 quad_perm:[2,3,0,1] row_mask:0xf bank_mask:0xf bound_ctrl:1
	v_pk_fma_f32 v[90:91], v[66:67], v[90:91], v[70:71]
	v_pk_mul_f32 v[94:95], v[94:95], v[96:97]
	v_mul_f32_e32 v98, 0xbfb8aa3b, v90
	v_mul_f32_e32 v99, 0xbfb8aa3b, v91
	v_exp_f32_e32 v98, v98
	v_exp_f32_e32 v99, v99
	v_add_f32_e32 v96, 1.0, v101
	v_add_f32_e32 v97, 1.0, v102
	v_add_f32_dpp v115, v115, v115 quad_perm:[2,3,0,1] row_mask:0xf bank_mask:0xf bound_ctrl:1
	v_add_f32_dpp v114, v114, v114 row_half_mirror row_mask:0xf bank_mask:0xf bound_ctrl:1
	v_rcp_f32_e32 v96, v96
	v_rcp_f32_e32 v97, v97
	v_add_f32_dpp v115, v115, v115 row_half_mirror row_mask:0xf bank_mask:0xf bound_ctrl:1
	v_add_f32_dpp v114, v114, v114 row_mirror row_mask:0xf bank_mask:0xf bound_ctrl:1
	v_add_f32_e32 v98, 1.0, v98
	v_add_f32_e32 v99, 1.0, v99
	v_add_f32_dpp v115, v115, v115 row_mirror row_mask:0xf bank_mask:0xf bound_ctrl:1
	v_rcp_f32_e32 v98, v98
	v_rcp_f32_e32 v99, v99
	v_readlane_b32 s27, v114, 48
	v_cvt_pk_bf16_f32 v92, v92, v93
	v_cvt_pk_bf16_f32 v93, v94, v95
	v_readlane_b32 s23, v114, 16
	v_mov_b32_e32 v95, s27
	v_readlane_b32 s27, v115, 16
	v_pk_mul_f32 v[88:89], v[88:89], v[96:97]
	v_readlane_b32 s42, v114, 0
	v_readlane_b32 s43, v114, 32
	v_mov_b32_e32 v94, s23
	v_readlane_b32 s23, v115, 0
	v_mov_b32_e32 v96, s27
	v_readlane_b32 s27, v115, 48
	v_pk_add_f32 v[94:95], s[42:43], v[94:95]
	v_add_f32_e32 v96, s23, v96
	v_readlane_b32 s23, v115, 32
	v_mov_b32_e32 v97, s27
	v_pk_mul_f32 v[90:91], v[90:91], v[98:99]
	v_add_f32_e32 v98, s23, v97
	v_mov_b32_e32 v97, v94
	v_mov_b32_e32 v99, v95
	v_pk_add_f32 v[94:95], v[96:97], v[98:99]
	v_cvt_pk_bf16_f32 v88, v88, v89
	v_pk_mul_f32 v[94:95], v[94:95], s[46:47] op_sel_hi:[1,0]
	v_cvt_pk_bf16_f32 v89, v90, v91
	v_fma_f32 v96, -v95, v95, v94
	v_max_f32_e32 v96, 0, v96
	v_add_f32_e32 v96, 0x3727c5ac, v96
	v_rsq_f32_e32 v96, v96
	v_pk_add_f32 v[84:85], v[84:85], v[94:95] op_sel:[0,1] neg_lo:[0,1] neg_hi:[0,1]
	v_pk_add_f32 v[86:87], v[86:87], v[94:95] op_sel:[0,1] neg_lo:[0,1] neg_hi:[0,1]
	ds_write2_b64 v122, v[92:93], v[88:89] offset0:132 offset1:198
	v_pk_mul_f32 v[84:85], v[84:85], v[96:97] op_sel_hi:[1,0]
	v_pk_mul_f32 v[86:87], v[86:87], v[96:97] op_sel_hi:[1,0]
	v_pk_fma_f32 v[84:85], v[64:65], v[84:85], v[68:69]
	v_pk_fma_f32 v[86:87], v[66:67], v[86:87], v[70:71]
	v_mul_f32_e32 v90, 0xbfb8aa3b, v84
	v_mul_f32_e32 v91, 0xbfb8aa3b, v85
	v_exp_f32_e32 v90, v90
	v_exp_f32_e32 v91, v91
	v_add_f32_dpp v116, v116, v116 quad_perm:[2,3,0,1] row_mask:0xf bank_mask:0xf bound_ctrl:1
	v_add_f32_dpp v117, v117, v117 quad_perm:[2,3,0,1] row_mask:0xf bank_mask:0xf bound_ctrl:1
	v_add_f32_e32 v88, 1.0, v90
	v_add_f32_e32 v89, 1.0, v91
	v_mul_f32_e32 v91, 0xbfb8aa3b, v87
	v_rcp_f32_e32 v88, v88
	v_rcp_f32_e32 v89, v89
	v_mul_f32_e32 v90, 0xbfb8aa3b, v86
	v_exp_f32_e32 v91, v91
	v_add_f32_dpp v116, v116, v116 row_half_mirror row_mask:0xf bank_mask:0xf bound_ctrl:1
	v_exp_f32_e32 v90, v90
	v_add_f32_dpp v117, v117, v117 row_half_mirror row_mask:0xf bank_mask:0xf bound_ctrl:1
	v_add_f32_dpp v116, v116, v116 row_mirror row_mask:0xf bank_mask:0xf bound_ctrl:1
	v_pk_mul_f32 v[84:85], v[84:85], v[88:89]
	v_add_f32_dpp v117, v117, v117 row_mirror row_mask:0xf bank_mask:0xf bound_ctrl:1
	v_readlane_b32 s27, v116, 48
	v_add_f32_e32 v89, 1.0, v91
	v_readlane_b32 s23, v116, 16
	v_mov_b32_e32 v91, s27
	v_readlane_b32 s27, v117, 16
	v_add_f32_e32 v88, 1.0, v90
	v_readlane_b32 s42, v116, 0
	v_readlane_b32 s43, v116, 32
	v_mov_b32_e32 v90, s23
	v_readlane_b32 s23, v117, 0
	v_mov_b32_e32 v92, s27
	v_readlane_b32 s27, v117, 48
	v_pk_add_f32 v[90:91], s[42:43], v[90:91]
	v_add_f32_e32 v92, s23, v92
	v_readlane_b32 s23, v117, 32
	v_mov_b32_e32 v93, s27
	v_mov_b32_e32 v95, v91
	v_add_f32_e32 v94, s23, v93
	v_mov_b32_e32 v93, v90
	v_pk_add_f32 v[90:91], v[92:93], v[94:95]
	v_rcp_f32_e32 v88, v88
	v_pk_mul_f32 v[90:91], v[90:91], s[46:47] op_sel_hi:[1,0]
	v_rcp_f32_e32 v89, v89
	v_fma_f32 v92, -v91, v91, v90
	v_max_f32_e32 v92, 0, v92
	v_add_f32_e32 v92, 0x3727c5ac, v92
	v_rsq_f32_e32 v92, v92
	v_pk_add_f32 v[80:81], v[80:81], v[90:91] op_sel:[0,1] neg_lo:[0,1] neg_hi:[0,1]
	v_cvt_pk_bf16_f32 v84, v84, v85
	v_pk_mul_f32 v[86:87], v[86:87], v[88:89]
	v_pk_mul_f32 v[80:81], v[80:81], v[92:93] op_sel_hi:[1,0]
	v_pk_add_f32 v[82:83], v[82:83], v[90:91] op_sel:[0,1] neg_lo:[0,1] neg_hi:[0,1]
	v_pk_fma_f32 v[80:81], v[64:65], v[80:81], v[68:69]
	v_pk_mul_f32 v[82:83], v[82:83], v[92:93] op_sel_hi:[1,0]
	v_mul_f32_e32 v85, 0xbfb8aa3b, v80
	v_exp_f32_e32 v88, v85
	v_mul_f32_e32 v85, 0xbfb8aa3b, v81
	v_exp_f32_e32 v89, v85
	v_pk_fma_f32 v[82:83], v[66:67], v[82:83], v[70:71]
	v_cvt_pk_bf16_f32 v85, v86, v87
	v_add_f32_e32 v86, 1.0, v88
	v_add_f32_e32 v87, 1.0, v89
	v_mul_f32_e32 v89, 0xbfb8aa3b, v83
	v_add_f32_dpp v118, v118, v118 quad_perm:[2,3,0,1] row_mask:0xf bank_mask:0xf bound_ctrl:1
	v_rcp_f32_e32 v86, v86
	v_rcp_f32_e32 v87, v87
	v_mul_f32_e32 v88, 0xbfb8aa3b, v82
	v_exp_f32_e32 v89, v89
	v_add_f32_dpp v119, v119, v119 quad_perm:[2,3,0,1] row_mask:0xf bank_mask:0xf bound_ctrl:1
	v_add_f32_dpp v118, v118, v118 row_half_mirror row_mask:0xf bank_mask:0xf bound_ctrl:1
	v_exp_f32_e32 v88, v88
	v_add_f32_dpp v119, v119, v119 row_half_mirror row_mask:0xf bank_mask:0xf bound_ctrl:1
	v_add_f32_dpp v118, v118, v118 row_mirror row_mask:0xf bank_mask:0xf bound_ctrl:1
	v_pk_mul_f32 v[80:81], v[80:81], v[86:87]
	v_add_f32_dpp v119, v119, v119 row_mirror row_mask:0xf bank_mask:0xf bound_ctrl:1
	v_readlane_b32 s27, v118, 48
	v_add_f32_e32 v87, 1.0, v89
	v_readlane_b32 s23, v118, 16
	v_mov_b32_e32 v89, s27
	v_readlane_b32 s27, v119, 16
	v_add_f32_e32 v86, 1.0, v88
	v_readlane_b32 s42, v118, 0
	v_readlane_b32 s43, v118, 32
	v_mov_b32_e32 v88, s23
	v_readlane_b32 s23, v119, 0
	v_mov_b32_e32 v90, s27
	v_readlane_b32 s27, v119, 48
	v_pk_add_f32 v[88:89], s[42:43], v[88:89]
	v_add_f32_e32 v90, s23, v90
	v_readlane_b32 s23, v119, 32
	v_mov_b32_e32 v91, s27
	v_mov_b32_e32 v93, v89
	v_add_f32_e32 v92, s23, v91
	v_mov_b32_e32 v91, v88
	v_pk_add_f32 v[88:89], v[90:91], v[92:93]
	v_rcp_f32_e32 v86, v86
	v_pk_mul_f32 v[88:89], v[88:89], s[46:47] op_sel_hi:[1,0]
	v_rcp_f32_e32 v87, v87
	v_fma_f32 v90, -v89, v89, v88
	v_max_f32_e32 v90, 0, v90
	v_add_f32_e32 v90, 0x3727c5ac, v90
	v_rsq_f32_e32 v90, v90
	v_pk_add_f32 v[76:77], v[76:77], v[88:89] op_sel:[0,1] neg_lo:[0,1] neg_hi:[0,1]
	v_cvt_pk_bf16_f32 v80, v80, v81
	v_pk_mul_f32 v[82:83], v[82:83], v[86:87]
	v_pk_mul_f32 v[76:77], v[76:77], v[90:91] op_sel_hi:[1,0]
	v_pk_add_f32 v[78:79], v[78:79], v[88:89] op_sel:[0,1] neg_lo:[0,1] neg_hi:[0,1]
	v_pk_fma_f32 v[76:77], v[64:65], v[76:77], v[68:69]
	v_add_f32_dpp v120, v120, v120 quad_perm:[2,3,0,1] row_mask:0xf bank_mask:0xf bound_ctrl:1
	v_mul_f32_e32 v81, 0xbfb8aa3b, v76
	v_exp_f32_e32 v86, v81
	v_mul_f32_e32 v81, 0xbfb8aa3b, v77
	v_exp_f32_e32 v87, v81
	v_cvt_pk_bf16_f32 v81, v82, v83
	v_add_f32_e32 v82, 1.0, v86
	v_rcp_f32_e32 v82, v82
	v_add_f32_e32 v83, 1.0, v87
	v_rcp_f32_e32 v83, v83
	v_pk_mul_f32 v[78:79], v[78:79], v[90:91] op_sel_hi:[1,0]
	v_add_f32_dpp v120, v120, v120 row_half_mirror row_mask:0xf bank_mask:0xf bound_ctrl:1
	v_pk_fma_f32 v[78:79], v[66:67], v[78:79], v[70:71]
	v_add_f32_dpp v121, v121, v121 row_mirror row_mask:0xf bank_mask:0xf bound_ctrl:1
	v_add_f32_dpp v120, v120, v120 row_mirror row_mask:0xf bank_mask:0xf bound_ctrl:1
	v_mul_f32_e32 v86, 0xbfb8aa3b, v78
	v_exp_f32_e32 v86, v86
	v_readlane_b32 s27, v120, 48
	v_add_u32_e32 v88, 0x800, v122
	v_pk_mul_f32 v[76:77], v[76:77], v[82:83]
	v_readlane_b32 s23, v120, 16
	v_mov_b32_e32 v83, s27
	v_readlane_b32 s27, v121, 16
	ds_write2_b64 v88, v[84:85], v[80:81] offset0:8 offset1:74
	v_readlane_b32 s42, v120, 0
	v_readlane_b32 s43, v120, 32
	v_mov_b32_e32 v82, s23
	v_readlane_b32 s23, v121, 0
	v_mov_b32_e32 v84, s27
	v_readlane_b32 s27, v121, 48
	v_pk_add_f32 v[82:83], s[42:43], v[82:83]
	v_add_f32_e32 v84, s23, v84
	v_readlane_b32 s23, v121, 32
	v_mov_b32_e32 v85, s27
	v_add_f32_e32 v80, 1.0, v86
	v_add_f32_e32 v86, s23, v85
	v_mov_b32_e32 v85, v82
	v_mov_b32_e32 v87, v83
	v_pk_add_f32 v[82:83], v[84:85], v[86:87]
	v_mul_f32_e32 v81, 0xbfb8aa3b, v79
	v_pk_mul_f32 v[82:83], v[82:83], s[46:47] op_sel_hi:[1,0]
	v_exp_f32_e32 v81, v81
	v_fma_f32 v84, -v83, v83, v82
	v_max_f32_e32 v84, 0, v84
	v_add_f32_e32 v84, 0x3727c5ac, v84
	v_rsq_f32_e32 v84, v84
	v_pk_add_f32 v[72:73], v[72:73], v[82:83] op_sel:[0,1] neg_lo:[0,1] neg_hi:[0,1]
	v_pk_add_f32 v[74:75], v[74:75], v[82:83] op_sel:[0,1] neg_lo:[0,1] neg_hi:[0,1]
	v_add_f32_e32 v81, 1.0, v81
	v_pk_mul_f32 v[72:73], v[72:73], v[84:85] op_sel_hi:[1,0]
	v_pk_mul_f32 v[74:75], v[74:75], v[84:85] op_sel_hi:[1,0]
	v_pk_fma_f32 v[64:65], v[64:65], v[72:73], v[68:69]
	v_pk_fma_f32 v[66:67], v[66:67], v[74:75], v[70:71]
	v_mul_f32_e32 v68, 0xbfb8aa3b, v64
	v_exp_f32_e32 v72, v68
	v_mul_f32_e32 v68, 0xbfb8aa3b, v65
	v_mul_f32_e32 v70, 0xbfb8aa3b, v66
	v_mul_f32_e32 v71, 0xbfb8aa3b, v67
	v_exp_f32_e32 v73, v68
	v_exp_f32_e32 v70, v70
	v_exp_f32_e32 v71, v71
	v_add_f32_e32 v72, 1.0, v72
	v_add_f32_e32 v73, 1.0, v73
	v_add_f32_e32 v70, 1.0, v70
	v_add_f32_e32 v71, 1.0, v71
	v_rcp_f32_e32 v80, v80
	v_rcp_f32_e32 v81, v81
	v_rcp_f32_e32 v72, v72
	v_rcp_f32_e32 v73, v73
	v_rcp_f32_e32 v70, v70
	v_rcp_f32_e32 v71, v71
	v_pk_mul_f32 v[68:69], v[78:79], v[80:81]
	v_pk_mul_f32 v[64:65], v[64:65], v[72:73]
	v_cvt_pk_bf16_f32 v74, v76, v77
	v_pk_mul_f32 v[66:67], v[66:67], v[70:71]
	v_cvt_pk_bf16_f32 v75, v68, v69
	v_cvt_pk_bf16_f32 v64, v64, v65
	v_cvt_pk_bf16_f32 v65, v66, v67
	ds_write2_b64 v88, v[74:75], v[64:65] offset0:140 offset1:206
	v_mul_u32_u24_e32 v64, 0x210, v158
	v_add3_u32 v108, 0, v148, v64
	s_waitcnt lgkmcnt(0)
	s_barrier
	ds_read_b128 v[64:67], v108
	ds_read_b128 v[68:71], v108 offset:64
	ds_read_b128 v[76:79], v108 offset:8448
	ds_read_b128 v[80:83], v108 offset:8512
	ds_read_b128 v[88:91], v108 offset:16896
	ds_read_b128 v[92:95], v108 offset:16960
	ds_read_b128 v[100:103], v108 offset:25344
	ds_read_b128 v[104:107], v108 offset:25408
	ds_read_b128 v[110:113], v108 offset:128
	ds_read_b128 v[114:117], v108 offset:192
	ds_read_b128 v[118:121], v108 offset:8576
	ds_read_b128 v[122:125], v108 offset:8640
	ds_read_b128 v[126:129], v108 offset:17024
	ds_read_b128 v[130:133], v108 offset:17088
	ds_read_b128 v[134:137], v108 offset:25472
	s_waitcnt lgkmcnt(14)
	ds_read_b128 v[138:141], v108 offset:25536
	v_mfma_f32_16x16x32_bf16 v[72:75], v[64:67], v[56:59], 0
	v_readlane_b32 s23, v254, 36
	v_mfma_f32_16x16x32_bf16 v[64:67], v[64:67], v[60:63], 0
	s_waitcnt lgkmcnt(13)
	ds_read_b128 v[142:145], v108 offset:256
	ds_read_b128 v[162:165], v108 offset:320
	v_mfma_f32_16x16x32_bf16 v[84:87], v[76:79], v[56:59], 0
	v_mfma_f32_16x16x32_bf16 v[76:79], v[76:79], v[60:63], 0
	s_waitcnt lgkmcnt(13)
	ds_read_b128 v[166:169], v108 offset:8704
	ds_read_b128 v[170:173], v108 offset:8768
	v_mfma_f32_16x16x32_bf16 v[96:99], v[88:91], v[56:59], 0
	v_mfma_f32_16x16x32_bf16 v[88:91], v[88:91], v[60:63], 0
	s_waitcnt lgkmcnt(13)
	ds_read_b128 v[174:177], v108 offset:17152
	ds_read_b128 v[178:181], v108 offset:17216
	v_mfma_f32_16x16x32_bf16 v[56:59], v[100:103], v[56:59], 0
	v_mfma_f32_16x16x32_bf16 v[60:63], v[100:103], v[60:63], 0
	v_mfma_f32_16x16x32_bf16 v[72:75], v[68:71], v[48:51], v[72:75]
	v_mfma_f32_16x16x32_bf16 v[64:67], v[68:71], v[52:55], v[64:67]
	v_mfma_f32_16x16x32_bf16 v[68:71], v[80:83], v[48:51], v[84:87]
	v_mfma_f32_16x16x32_bf16 v[76:79], v[80:83], v[52:55], v[76:79]
	v_mfma_f32_16x16x32_bf16 v[80:83], v[92:95], v[48:51], v[96:99]
	v_mfma_f32_16x16x32_bf16 v[84:87], v[92:95], v[52:55], v[88:91]
	s_waitcnt lgkmcnt(14)
	ds_read_b128 v[182:185], v108 offset:25600
	v_mfma_f32_16x16x32_bf16 v[48:51], v[104:107], v[48:51], v[56:59]
	v_mfma_f32_16x16x32_bf16 v[52:55], v[104:107], v[52:55], v[60:63]
	s_nop 1
	s_waitcnt lgkmcnt(14)
	ds_read_b128 v[186:189], v108 offset:25664
	v_mfma_f32_16x16x32_bf16 v[72:75], v[110:113], v[40:43], v[72:75]
	v_mfma_f32_16x16x32_bf16 v[56:59], v[110:113], v[44:47], v[64:67]
	s_nop 2
	s_waitcnt lgkmcnt(13)
	ds_read_b128 v[190:193], v108 offset:384
	ds_read_b128 v[194:197], v108 offset:448
	v_mfma_f32_16x16x32_bf16 v[68:71], v[118:121], v[40:43], v[68:71]
	v_mfma_f32_16x16x32_bf16 v[64:67], v[118:121], v[44:47], v[76:79]
	s_nop 2
	s_waitcnt lgkmcnt(13)
	ds_read_b128 v[198:201], v108 offset:8832
	ds_read_b128 v[202:205], v108 offset:8896
	v_mfma_f32_16x16x32_bf16 v[80:83], v[126:129], v[40:43], v[80:83]
	v_mfma_f32_16x16x32_bf16 v[76:79], v[126:129], v[44:47], v[84:87]
	s_nop 2
	s_waitcnt lgkmcnt(13)
	ds_read_b128 v[206:209], v108 offset:17280
	ds_read_b128 v[218:221], v108 offset:17344
	v_mfma_f32_16x16x32_bf16 v[40:43], v[134:137], v[40:43], v[48:51]
	v_mfma_f32_16x16x32_bf16 v[44:47], v[134:137], v[44:47], v[52:55]
	v_mfma_f32_16x16x32_bf16 v[48:51], v[114:117], v[32:35], v[72:75]
	v_mfma_f32_16x16x32_bf16 v[52:55], v[114:117], v[36:39], v[56:59]
	v_mfma_f32_16x16x32_bf16 v[56:59], v[122:125], v[32:35], v[68:71]
	v_mfma_f32_16x16x32_bf16 v[60:63], v[122:125], v[36:39], v[64:67]
	v_mfma_f32_16x16x32_bf16 v[64:67], v[130:133], v[32:35], v[80:83]
	v_mfma_f32_16x16x32_bf16 v[68:71], v[130:133], v[36:39], v[76:79]
	s_waitcnt lgkmcnt(14)
	ds_read_b128 v[222:225], v108 offset:25728
	v_mfma_f32_16x16x32_bf16 v[32:35], v[138:141], v[32:35], v[40:43]
	v_mfma_f32_16x16x32_bf16 v[36:39], v[138:141], v[36:39], v[44:47]
	s_nop 1
	s_waitcnt lgkmcnt(14)
	ds_read_b128 v[226:229], v108 offset:25792
	v_mfma_f32_16x16x32_bf16 v[48:51], v[142:145], v[24:27], v[48:51]
	v_mfma_f32_16x16x32_bf16 v[40:43], v[142:145], v[28:31], v[52:55]
	s_nop 2
	s_waitcnt lgkmcnt(13)
	v_mfma_f32_16x16x32_bf16 v[56:59], v[166:169], v[24:27], v[56:59]
	v_mfma_f32_16x16x32_bf16 v[52:55], v[166:169], v[28:31], v[60:63]
	s_nop 2
	s_waitcnt lgkmcnt(11)
	v_mfma_f32_16x16x32_bf16 v[64:67], v[174:177], v[24:27], v[64:67]
	v_mfma_f32_16x16x32_bf16 v[60:63], v[174:177], v[28:31], v[68:71]
	s_nop 2
	s_waitcnt lgkmcnt(9)
	v_mfma_f32_16x16x32_bf16 v[24:27], v[182:185], v[24:27], v[32:35]
	v_mfma_f32_16x16x32_bf16 v[28:31], v[182:185], v[28:31], v[36:39]
	v_mfma_f32_16x16x32_bf16 v[32:35], v[162:165], v[16:19], v[48:51]
	v_mfma_f32_16x16x32_bf16 v[36:39], v[162:165], v[20:23], v[40:43]
	v_mfma_f32_16x16x32_bf16 v[40:43], v[170:173], v[16:19], v[56:59]
	v_mfma_f32_16x16x32_bf16 v[44:47], v[170:173], v[20:23], v[52:55]
	v_mfma_f32_16x16x32_bf16 v[48:51], v[178:181], v[16:19], v[64:67]
	v_mfma_f32_16x16x32_bf16 v[52:55], v[178:181], v[20:23], v[60:63]
	s_waitcnt lgkmcnt(8)
	v_mfma_f32_16x16x32_bf16 v[16:19], v[186:189], v[16:19], v[24:27]
	v_mfma_f32_16x16x32_bf16 v[20:23], v[186:189], v[20:23], v[28:31]
	s_nop 1
	s_waitcnt lgkmcnt(7)
	v_mfma_f32_16x16x32_bf16 v[32:35], v[190:193], v[8:11], v[32:35]
	v_mfma_f32_16x16x32_bf16 v[24:27], v[190:193], v[12:15], v[36:39]
	s_nop 2
	s_waitcnt lgkmcnt(5)
	v_mfma_f32_16x16x32_bf16 v[40:43], v[198:201], v[8:11], v[40:43]
	v_mfma_f32_16x16x32_bf16 v[36:39], v[198:201], v[12:15], v[44:47]
	s_nop 2
	s_waitcnt lgkmcnt(3)
	v_mfma_f32_16x16x32_bf16 v[48:51], v[206:209], v[8:11], v[48:51]
	v_mfma_f32_16x16x32_bf16 v[44:47], v[206:209], v[12:15], v[52:55]
	s_nop 2
	s_waitcnt lgkmcnt(1)
	v_mfma_f32_16x16x32_bf16 v[68:71], v[222:225], v[8:11], v[16:19]
	v_mfma_f32_16x16x32_bf16 v[32:35], v[194:197], v[4:7], v[32:35]
	v_mfma_f32_16x16x32_bf16 v[16:19], v[194:197], v[0:3], v[24:27]
	v_or_b32_e32 v28, s26, v158
	v_lshlrev_b32_e32 v29, 7, v156
	v_and_b32_e32 v29, 0x1800, v29
	v_lshlrev_b32_e32 v28, 1, v28
	v_add3_u32 v30, s23, v28, v29
	v_mfma_f32_16x16x32_bf16 v[52:55], v[222:225], v[12:15], v[20:23]
	v_readlane_b32 s26, v254, 37
	v_mfma_f32_16x16x32_bf16 v[24:27], v[202:205], v[4:7], v[40:43]
	v_mfma_f32_16x16x32_bf16 v[12:15], v[202:205], v[0:3], v[36:39]
	ds_read_u16 v31, v30
	s_nop 1
	ds_read_u16 v36, v30 offset:512
	ds_read_u16 v37, v30 offset:1024
	ds_read_u16 v38, v30 offset:1536
	ds_read_u16 v39, v30 offset:8192
	ds_read_u16 v40, v30 offset:8704
	ds_read_u16 v41, v30 offset:9216
	ds_read_u16 v42, v30 offset:9728
	s_waitcnt lgkmcnt(7)
	v_lshlrev_b32_e32 v31, 16, v31
	v_mul_f32_e32 v43, 0xbfb8aa3b, v31
	v_exp_f32_e32 v43, v43
	s_waitcnt lgkmcnt(6)
	v_lshlrev_b32_e32 v36, 16, v36
	v_mfma_f32_16x16x32_bf16 v[8:11], v[218:221], v[0:3], v[44:47]
	s_waitcnt lgkmcnt(5)
	v_lshlrev_b32_e32 v37, 16, v37
	v_add_f32_e32 v43, 1.0, v43
	v_rcp_f32_e32 v43, v43
	v_mul_f32_e32 v44, 0xbfb8aa3b, v36
	v_exp_f32_e32 v44, v44
	v_mfma_f32_16x16x32_bf16 v[20:23], v[218:221], v[4:7], v[48:51]
	v_mul_f32_e32 v31, v43, v31
	v_mul_f32_e32 v31, v32, v31
	v_add_f32_e32 v32, 1.0, v44
	v_rcp_f32_e32 v32, v32
	v_mul_f32_e32 v43, 0xbfb8aa3b, v37
	v_exp_f32_e32 v43, v43
	v_cvt_pk_bf16_f32 v31, v31, s0
	ds_write_b16 v30, v31
	v_mul_f32_e32 v31, v32, v36
	v_mul_f32_e32 v31, v33, v31
	s_waitcnt lgkmcnt(5)
	v_lshlrev_b32_e32 v33, 16, v38
	v_add_f32_e32 v32, 1.0, v43
	v_mul_f32_e32 v36, 0xbfb8aa3b, v33
	v_rcp_f32_e32 v32, v32
	v_exp_f32_e32 v36, v36
	v_cvt_pk_bf16_f32 v31, v31, s0
	ds_write_b16 v30, v31 offset:512
	v_mul_f32_e32 v31, v32, v37
	v_add_f32_e32 v32, 1.0, v36
	v_rcp_f32_e32 v32, v32
	v_mul_f32_e32 v31, v34, v31
	v_cvt_pk_bf16_f32 v31, v31, s0
	ds_write_b16 v30, v31 offset:1024
	v_mul_f32_e32 v31, v32, v33
	s_waitcnt lgkmcnt(6)
	v_lshlrev_b32_e32 v32, 16, v39
	v_mul_f32_e32 v33, 0xbfb8aa3b, v32
	v_exp_f32_e32 v33, v33
	v_mul_f32_e32 v31, v35, v31
	v_cvt_pk_bf16_f32 v31, v31, s0
	ds_write_b16 v30, v31 offset:1536
	v_add_f32_e32 v31, 1.0, v33
	s_waitcnt lgkmcnt(6)
	v_lshlrev_b32_e32 v33, 16, v40
	v_rcp_f32_e32 v31, v31
	v_mul_f32_e32 v34, 0xbfb8aa3b, v33
	v_exp_f32_e32 v34, v34
	v_mfma_f32_16x16x32_bf16 v[4:7], v[226:229], v[4:7], v[68:71]
	v_mul_f32_e32 v31, v31, v32
	v_mul_f32_e32 v24, v24, v31
	v_add_f32_e32 v31, 1.0, v34
	s_waitcnt lgkmcnt(5)
	v_lshlrev_b32_e32 v32, 16, v41
	v_rcp_f32_e32 v31, v31
	v_mul_f32_e32 v34, 0xbfb8aa3b, v32
	v_exp_f32_e32 v34, v34
	v_cvt_pk_bf16_f32 v24, v24, s0
	ds_write_b16 v30, v24 offset:8192
	v_mul_f32_e32 v24, v31, v33
	s_waitcnt lgkmcnt(5)
	v_lshlrev_b32_e32 v31, 16, v42
	v_mul_f32_e32 v24, v25, v24
	v_add_f32_e32 v25, 1.0, v34
	v_mul_f32_e32 v33, 0xbfb8aa3b, v31
	v_rcp_f32_e32 v25, v25
	v_exp_f32_e32 v33, v33
	v_cvt_pk_bf16_f32 v24, v24, s0
	ds_write_b16 v30, v24 offset:8704
	v_mul_f32_e32 v24, v25, v32
	v_add_f32_e32 v25, 1.0, v33
	v_rcp_f32_e32 v25, v25
	v_mul_f32_e32 v24, v26, v24
	v_cvt_pk_bf16_f32 v24, v24, s0
	ds_write_b16 v30, v24 offset:9216
	v_mul_f32_e32 v24, v25, v31
	ds_read_u16 v25, v30 offset:16384
	ds_read_u16 v26, v30 offset:16896
	ds_read_u16 v31, v30 offset:17408
	ds_read_u16 v32, v30 offset:17920
	ds_read_u16 v33, v30 offset:24576
	ds_read_u16 v34, v30 offset:25088
	ds_read_u16 v35, v30 offset:25600
	ds_read_u16 v36, v30 offset:26112
	s_waitcnt lgkmcnt(7)
	v_lshlrev_b32_e32 v25, 16, v25
	v_mul_f32_e32 v37, 0xbfb8aa3b, v25
	v_exp_f32_e32 v37, v37
	v_mul_f32_e32 v24, v27, v24
	v_cvt_pk_bf16_f32 v24, v24, s0
	ds_write_b16 v30, v24 offset:9728
	v_add_f32_e32 v24, 1.0, v37
	s_waitcnt lgkmcnt(7)
	v_lshlrev_b32_e32 v26, 16, v26
	v_rcp_f32_e32 v24, v24
	v_mul_f32_e32 v27, 0xbfb8aa3b, v26
	v_exp_f32_e32 v27, v27
	v_mfma_f32_16x16x32_bf16 v[0:3], v[226:229], v[0:3], v[52:55]
	v_mul_f32_e32 v24, v24, v25
	v_mul_f32_e32 v20, v20, v24
	v_add_f32_e32 v24, 1.0, v27
	s_waitcnt lgkmcnt(6)
	v_lshlrev_b32_e32 v25, 16, v31
	v_rcp_f32_e32 v24, v24
	v_mul_f32_e32 v27, 0xbfb8aa3b, v25
	v_exp_f32_e32 v27, v27
	v_cvt_pk_bf16_f32 v20, v20, s0
	ds_write_b16 v30, v20 offset:16384
	v_mul_f32_e32 v20, v24, v26
	s_waitcnt lgkmcnt(6)
	v_lshlrev_b32_e32 v24, 16, v32
	v_mul_f32_e32 v20, v21, v20
	v_add_f32_e32 v21, 1.0, v27
	v_mul_f32_e32 v26, 0xbfb8aa3b, v24
	v_rcp_f32_e32 v21, v21
	v_exp_f32_e32 v26, v26
	v_cvt_pk_bf16_f32 v20, v20, s0
	ds_write_b16 v30, v20 offset:16896
	v_mul_f32_e32 v20, v21, v25
	v_add_f32_e32 v21, 1.0, v26
	v_rcp_f32_e32 v21, v21
	v_mul_f32_e32 v20, v22, v20
	v_cvt_pk_bf16_f32 v20, v20, s0
	ds_write_b16 v30, v20 offset:17408
	v_mul_f32_e32 v20, v21, v24
	s_waitcnt lgkmcnt(7)
	v_lshlrev_b32_e32 v21, 16, v33
	v_mul_f32_e32 v22, 0xbfb8aa3b, v21
	v_exp_f32_e32 v22, v22
	v_mul_f32_e32 v20, v23, v20
	v_cvt_pk_bf16_f32 v20, v20, s0
	ds_write_b16 v30, v20 offset:17920
	v_add_f32_e32 v20, 1.0, v22
	s_waitcnt lgkmcnt(7)
	v_lshlrev_b32_e32 v22, 16, v34
	v_rcp_f32_e32 v20, v20
	v_mul_f32_e32 v23, 0xbfb8aa3b, v22
	v_exp_f32_e32 v23, v23
	v_mul_f32_e32 v20, v20, v21
	v_mul_f32_e32 v4, v4, v20
	v_add_f32_e32 v20, 1.0, v23
	s_waitcnt lgkmcnt(6)
	v_lshlrev_b32_e32 v21, 16, v35
	v_rcp_f32_e32 v20, v20
	v_mul_f32_e32 v23, 0xbfb8aa3b, v21
	v_exp_f32_e32 v23, v23
	v_cvt_pk_bf16_f32 v4, v4, s0
	ds_write_b16 v30, v4 offset:24576
	v_mul_f32_e32 v4, v20, v22
	s_waitcnt lgkmcnt(6)
	v_lshlrev_b32_e32 v20, 16, v36
	v_mul_f32_e32 v4, v5, v4
	v_add_f32_e32 v5, 1.0, v23
	v_mul_f32_e32 v22, 0xbfb8aa3b, v20
	v_rcp_f32_e32 v5, v5
	v_exp_f32_e32 v22, v22
	v_cvt_pk_bf16_f32 v4, v4, s0
	ds_write_b16 v30, v4 offset:25088
	v_mul_f32_e32 v4, v5, v21
	v_add_f32_e32 v5, 1.0, v22
	v_rcp_f32_e32 v5, v5
	v_mul_f32_e32 v4, v6, v4
	v_cvt_pk_bf16_f32 v4, v4, s0
	ds_write_b16 v30, v4 offset:25600
	v_mul_f32_e32 v4, v5, v20
	v_add3_u32 v5, s26, v28, v29
	ds_read_u16 v6, v5
	ds_read_u16 v20, v5 offset:512
	ds_read_u16 v21, v5 offset:1024
	ds_read_u16 v22, v5 offset:1536
	ds_read_u16 v23, v5 offset:8192
	ds_read_u16 v24, v5 offset:8704
	ds_read_u16 v25, v5 offset:9216
	ds_read_u16 v26, v5 offset:9728
	s_waitcnt lgkmcnt(7)
	v_lshlrev_b32_e32 v6, 16, v6
	v_mul_f32_e32 v27, 0xbfb8aa3b, v6
	v_exp_f32_e32 v27, v27
	v_mul_f32_e32 v4, v7, v4
	v_cvt_pk_bf16_f32 v4, v4, s0
	ds_write_b16 v30, v4 offset:26112
	v_add_f32_e32 v4, 1.0, v27
	s_waitcnt lgkmcnt(7)
	v_lshlrev_b32_e32 v7, 16, v20
	v_rcp_f32_e32 v4, v4
	v_mul_f32_e32 v20, 0xbfb8aa3b, v7
	v_exp_f32_e32 v20, v20
	v_readlane_b32 s26, v255, 9
	v_mul_f32_e32 v4, v4, v6
	v_mul_f32_e32 v4, v16, v4
	v_add_f32_e32 v6, 1.0, v20
	s_waitcnt lgkmcnt(6)
	v_lshlrev_b32_e32 v16, 16, v21
	v_rcp_f32_e32 v6, v6
	v_mul_f32_e32 v20, 0xbfb8aa3b, v16
	v_exp_f32_e32 v20, v20
	v_cvt_pk_bf16_f32 v4, v4, s0
	ds_write_b16 v5, v4
	v_mul_f32_e32 v4, v6, v7
	s_waitcnt lgkmcnt(6)
	v_lshlrev_b32_e32 v7, 16, v22
	v_mul_f32_e32 v4, v17, v4
	v_add_f32_e32 v6, 1.0, v20
	v_mul_f32_e32 v17, 0xbfb8aa3b, v7
	v_rcp_f32_e32 v6, v6
	v_exp_f32_e32 v17, v17
	v_cvt_pk_bf16_f32 v4, v4, s0
	ds_write_b16 v5, v4 offset:512
	v_mul_f32_e32 v4, v6, v16
	v_add_f32_e32 v6, 1.0, v17
	v_rcp_f32_e32 v6, v6
	v_mul_f32_e32 v4, v18, v4
	v_cvt_pk_bf16_f32 v4, v4, s0
	ds_write_b16 v5, v4 offset:1024
	v_mul_f32_e32 v4, v6, v7
	s_waitcnt lgkmcnt(7)
	v_lshlrev_b32_e32 v6, 16, v23
	v_mul_f32_e32 v7, 0xbfb8aa3b, v6
	v_exp_f32_e32 v7, v7
	v_mul_f32_e32 v4, v19, v4
	v_cvt_pk_bf16_f32 v4, v4, s0
	ds_write_b16 v5, v4 offset:1536
	v_add_f32_e32 v4, 1.0, v7
	s_waitcnt lgkmcnt(7)
	v_lshlrev_b32_e32 v7, 16, v24
	v_rcp_f32_e32 v4, v4
	v_mul_f32_e32 v16, 0xbfb8aa3b, v7
	v_exp_f32_e32 v16, v16
	v_readlane_b32 s27, v255, 10
	v_mul_f32_e32 v4, v4, v6
	v_mul_f32_e32 v4, v12, v4
	v_add_f32_e32 v6, 1.0, v16
	s_waitcnt lgkmcnt(6)
	v_lshlrev_b32_e32 v12, 16, v25
	v_rcp_f32_e32 v6, v6
	v_mul_f32_e32 v16, 0xbfb8aa3b, v12
	v_exp_f32_e32 v16, v16
	v_cvt_pk_bf16_f32 v4, v4, s0
	ds_write_b16 v5, v4 offset:8192
	v_mul_f32_e32 v4, v6, v7
	s_waitcnt lgkmcnt(6)
	v_lshlrev_b32_e32 v7, 16, v26
	v_mul_f32_e32 v4, v13, v4
	v_add_f32_e32 v6, 1.0, v16
	v_mul_f32_e32 v13, 0xbfb8aa3b, v7
	v_rcp_f32_e32 v6, v6
	v_exp_f32_e32 v13, v13
	v_cvt_pk_bf16_f32 v4, v4, s0
	ds_write_b16 v5, v4 offset:8704
	v_mul_f32_e32 v4, v6, v12
	v_add_f32_e32 v6, 1.0, v13
	v_rcp_f32_e32 v6, v6
	v_mul_f32_e32 v4, v14, v4
	v_cvt_pk_bf16_f32 v4, v4, s0
	ds_write_b16 v5, v4 offset:9216
	v_mul_f32_e32 v4, v6, v7
	ds_read_u16 v6, v5 offset:16384
	ds_read_u16 v7, v5 offset:16896
	ds_read_u16 v12, v5 offset:17408
	ds_read_u16 v13, v5 offset:17920
	ds_read_u16 v14, v5 offset:24576
	ds_read_u16 v16, v5 offset:25088
	ds_read_u16 v17, v5 offset:25600
	ds_read_u16 v18, v5 offset:26112
	s_waitcnt lgkmcnt(7)
	v_lshlrev_b32_e32 v6, 16, v6
	v_mul_f32_e32 v19, 0xbfb8aa3b, v6
	v_exp_f32_e32 v19, v19
	v_mul_f32_e32 v4, v15, v4
	v_cvt_pk_bf16_f32 v4, v4, s0
	ds_write_b16 v5, v4 offset:9728
	v_add_f32_e32 v4, 1.0, v19
	s_waitcnt lgkmcnt(7)
	v_lshlrev_b32_e32 v7, 16, v7
	v_rcp_f32_e32 v4, v4
	v_mul_f32_e32 v15, 0xbfb8aa3b, v7
	v_exp_f32_e32 v15, v15
	v_mul_f32_e32 v4, v4, v6
	v_mul_f32_e32 v4, v8, v4
	v_add_f32_e32 v6, 1.0, v15
	s_waitcnt lgkmcnt(6)
	v_lshlrev_b32_e32 v8, 16, v12
	v_rcp_f32_e32 v6, v6
	v_mul_f32_e32 v12, 0xbfb8aa3b, v8
	v_exp_f32_e32 v12, v12
	v_cvt_pk_bf16_f32 v4, v4, s0
	ds_write_b16 v5, v4 offset:16384
	v_mul_f32_e32 v4, v6, v7
	s_waitcnt lgkmcnt(6)
	v_lshlrev_b32_e32 v7, 16, v13
	v_mul_f32_e32 v4, v9, v4
	v_add_f32_e32 v6, 1.0, v12
	v_mul_f32_e32 v9, 0xbfb8aa3b, v7
	v_rcp_f32_e32 v6, v6
	v_exp_f32_e32 v9, v9
	v_cvt_pk_bf16_f32 v4, v4, s0
	ds_write_b16 v5, v4 offset:16896
	v_mul_f32_e32 v4, v6, v8
	v_add_f32_e32 v6, 1.0, v9
	v_rcp_f32_e32 v6, v6
	v_mul_f32_e32 v4, v10, v4
	v_cvt_pk_bf16_f32 v4, v4, s0
	ds_write_b16 v5, v4 offset:17408
	v_mul_f32_e32 v4, v6, v7
	s_waitcnt lgkmcnt(7)
	v_lshlrev_b32_e32 v6, 16, v14
	v_mul_f32_e32 v7, 0xbfb8aa3b, v6
	v_exp_f32_e32 v7, v7
	v_mul_f32_e32 v4, v11, v4
	v_cvt_pk_bf16_f32 v4, v4, s0
	ds_write_b16 v5, v4 offset:17920
	v_add_f32_e32 v4, 1.0, v7
	s_waitcnt lgkmcnt(7)
	v_lshlrev_b32_e32 v7, 16, v16
	v_rcp_f32_e32 v4, v4
	v_mul_f32_e32 v8, 0xbfb8aa3b, v7
	v_exp_f32_e32 v8, v8
	v_mul_f32_e32 v4, v4, v6
	v_mul_f32_e32 v0, v0, v4
	v_add_f32_e32 v4, 1.0, v8
	s_waitcnt lgkmcnt(6)
	v_lshlrev_b32_e32 v6, 16, v17
	v_rcp_f32_e32 v4, v4
	v_mul_f32_e32 v8, 0xbfb8aa3b, v6
	v_exp_f32_e32 v8, v8
	v_cvt_pk_bf16_f32 v0, v0, s0
	ds_write_b16 v5, v0 offset:24576
	v_mul_f32_e32 v0, v4, v7
	s_waitcnt lgkmcnt(6)
	v_lshlrev_b32_e32 v4, 16, v18
	v_mul_f32_e32 v0, v1, v0
	v_add_f32_e32 v1, 1.0, v8
	v_mul_f32_e32 v7, 0xbfb8aa3b, v4
	v_rcp_f32_e32 v1, v1
	v_exp_f32_e32 v7, v7
	v_cvt_pk_bf16_f32 v0, v0, s0
	ds_write_b16 v5, v0 offset:25088
	v_mul_f32_e32 v0, v1, v6
	v_add_f32_e32 v1, 1.0, v7
	v_rcp_f32_e32 v1, v1
	v_mul_f32_e32 v0, v2, v0
	v_cvt_pk_bf16_f32 v0, v0, s0
	ds_write_b16 v5, v0 offset:25600
	v_mul_f32_e32 v0, v1, v4
	v_mul_f32_e32 v0, v3, v0
	v_cvt_pk_bf16_f32 v0, v0, s0
	ds_write_b16 v5, v0 offset:26112
	v_ashrrev_i32_e32 v0, 31, v156
	v_lshrrev_b32_e32 v0, 27, v0
	v_add_u32_e32 v0, v156, v0
	v_ashrrev_i32_e32 v8, 5, v0
	v_and_b32_e32 v0, 0xffffffe0, v0
	v_sub_u32_e32 v2, v156, v0
	v_lshlrev_b32_e32 v0, 3, v2
	v_add_u32_e32 v6, s65, v8
	v_ashrrev_i32_e32 v1, 31, v0
	v_ashrrev_i32_e32 v7, 31, v6
	v_lshl_add_u64 v[4:5], v[0:1], 1, s[26:27]
	v_lshl_add_u32 v9, v2, 4, s23
	v_lshlrev_b64 v[6:7], 11, v[6:7]
	v_lshl_add_u32 v0, v8, 9, v9
	v_lshl_add_u64 v[6:7], v[4:5], 0, v[6:7]
	s_waitcnt lgkmcnt(0)
	s_barrier
	ds_read_b128 v[28:31], v0
	ds_read_b128 v[16:19], v0 offset:8192
	ds_read_b128 v[20:23], v0 offset:16384
	ds_read_b128 v[24:27], v0 offset:24576
	s_waitcnt lgkmcnt(3)
	global_store_dwordx4 v[6:7], v[28:31], off sc1
	s_nop 1
	v_add_u32_e32 v6, 16, v8
	v_lshl_add_u32 v0, v6, 9, v9
	v_add_u32_e32 v6, s65, v6
	v_ashrrev_i32_e32 v7, 31, v6
	v_lshlrev_b64 v[6:7], 11, v[6:7]
	v_lshl_add_u64 v[6:7], v[4:5], 0, v[6:7]
	s_waitcnt lgkmcnt(2)
	global_store_dwordx4 v[6:7], v[16:19], off sc1
	s_nop 1
	v_add_u32_e32 v6, 32, v8
	v_lshl_add_u32 v0, v6, 9, v9
	v_add_u32_e32 v6, s65, v6
	v_ashrrev_i32_e32 v7, 31, v6
	v_lshlrev_b64 v[6:7], 11, v[6:7]
	v_lshl_add_u64 v[6:7], v[4:5], 0, v[6:7]
	s_waitcnt lgkmcnt(1)
	global_store_dwordx4 v[6:7], v[20:23], off sc1
	s_nop 1
	v_add_u32_e32 v6, 48, v8
	v_lshl_add_u32 v0, v6, 9, v9
	v_add_u32_e32 v6, s65, v6
	v_ashrrev_i32_e32 v7, 31, v6
	v_lshlrev_b64 v[6:7], 11, v[6:7]
	v_lshl_add_u64 v[4:5], v[4:5], 0, v[6:7]
	s_waitcnt lgkmcnt(0)
	global_store_dwordx4 v[4:5], v[24:27], off sc1
	s_nop 1
	s_mov_b64 s[26:27], 0
	s_barrier
